# attention loop regenerated as 8-wave ping-pong: matrix phase (PV prev + QK) and vector phase (softmax) each end in s_barrier, waves 4-7 run one phase behind waves 0-3; reference folded into MFMA SrcC;
# baseline (speedup 1.0000x reference)
; #define LAS3 __attribute__((address_space(3)))
; __global__ void __launch_bounds__(NT, 2) fwd_megakernel(Params p) {
;   extern __shared__ __attribute__((aligned(16))) char smem[];
;   cg::grid_group grid = cg::this_grid();
;   volatile LAS3 unsigned* xst = (volatile LAS3 unsigned*)(LAS3 unsigned*)(smem + SMEM_BYTES - 16);
;   if (threadIdx.x == 0) { xst[0] = 0u; xst[1] = 0u; xst[2] = 0u; xst[3] = 0u; }
;   __syncthreads();
;   if (blockIdx.x == 0) { unsigned* bw = (unsigned*)(p.ws + OFF_BAR); for (int i = threadIdx.x; i < (int)(BAR_BYTES / 4); i += NT) bw[i] = 0u; }
_Z14fwd_megakernel6Params:
	v_readfirstlane_b32 s100, v0
	s_nop 3
	s_bfe_u32 s100, s100, 0x10008
	s_load_dwordx8 s[4:11], s[0:1], 0xc0
	s_load_dword s18, s[0:1], 0xf8
	s_load_dwordx4 s[92:95], s[0:1], 0xe0
	s_load_dwordx2 s[96:97], s[0:1], 0xf0
	s_add_u32 s24, s0, 0xf0
	s_addc_u32 s25, s1, 0
	v_and_b32_e32 v192, 0x3ff, v0
	s_waitcnt lgkmcnt(0)
	v_writelane_b32 v249, s4, 0
	s_nop 1
	v_writelane_b32 v249, s5, 1
	v_writelane_b32 v249, s6, 2
	v_writelane_b32 v249, s7, 3
	v_writelane_b32 v249, s8, 4
	v_writelane_b32 v249, s9, 5
	v_writelane_b32 v249, s10, 6
	v_writelane_b32 v249, s11, 7
	v_cmp_eq_u32_e64 s[6:7], 0, v192
	s_mov_b64 s[4:5], exec
	s_nop 0
	v_writelane_b32 v249, s6, 8
	s_nop 1
	v_writelane_b32 v249, s7, 9
	s_and_b64 s[6:7], s[4:5], s[6:7]
	s_mov_b64 exec, s[6:7]
	s_cbranch_execz .LBB0_2
	s_add_i32 s3, 0, 0x20ff0
	v_mov_b32_e32 v1, 0
	v_mov_b32_e32 v2, s3
	s_add_i32 s3, 0, 0x20ff4
	ds_write_b32 v2, v1
	v_mov_b32_e32 v2, s3
	s_add_i32 s3, 0, 0x20ff8
	ds_write_b32 v2, v1
	v_mov_b32_e32 v2, s3
	s_add_i32 s3, 0, 0x20ffc
	ds_write_b32 v2, v1
	v_mov_b32_e32 v2, s3
	ds_write_b32 v2, v1

; DI float bflo(unsigned u) { return __uint_as_float(u << 16); }
; DI float bfhi(unsigned u) { return __uint_as_float(u & 0xffff0000u); }
; DI f32x16 zero16() { f32x16 z; for (int i = 0; i < 16; ++i) z[i] = 0.f; return z; }
; DI void phase_attn(const Params& p, int hf, bool skipctx, char* smem, int& rot) {
;     ...
;       for (int ks = 0; ks < 6; ++ks) qu[ks] = *(const uint4*)(Qb + tq * 768 + head * 96 + ks * 16 + h * 8);
; #pragma unroll
;       for (int ks = 0; ks < 4; ++ks) {
;         const uint4 u = qu[ks];
;         qf[ks] = pack8(bflo(u.x) * QSCALE, bfhi(u.x) * QSCALE, bflo(u.y) * QSCALE, bfhi(u.y) * QSCALE, bflo(u.z) * QSCALE, bfhi(u.z) * QSCALE, bflo(u.w) * QSCALE, bfhi(u.w) * QSCALE);
;       }
;       const unsigned a1[4] = {qu[4].x, qu[4].y, qu[4].z, qu[4].w}, a2[4] = {qu[5].x, qu[5].y, qu[5].z, qu[5].w};
;       float o1[8], o2[8];
;       const int sq_ = s0 + w * 32 + r;
; #pragma unroll
;       for (int e = 0; e < 8; ++e) {
;         const float x1 = ((e & 1) ? bfhi(a1[e >> 1]) : bflo(a1[e >> 1])) * QSCALE;
;         const float x2 = ((e & 1) ? bfhi(a2[e >> 1]) : bflo(a2[e >> 1])) * QSCALE;
;         float cs = 1.f, sn = 0.f;
;         if (sq_ >= LC) { cs = axc[(sq_ - LC) * 16 + 8 * h + e]; sn = axs[(sq_ - LC) * 16 + 8 * h + e]; }
;         o1[e] = x1 * cs - x2 * sn; o2[e] = x1 * sn + x2 * cs;
;       }
;       qf[4] = pack8(o1[0], o1[1], o1[2], o1[3], o1[4], o1[5], o1[6], o1[7]);
;       qf[5] = pack8(o2[0], o2[1], o2[2], o2[3], o2[4], o2[5], o2[6], o2[7]);
;     }
;     const bf16_t* Kg = Kb + (size_t)(bl * 8 + head) * S * 96;
;     const bf16_t* Vg = VTb + (size_t)(bl * 8 + head) * 64 * S;
;     f32x16 o[2]; o[0] = zero16(); o[1] = zero16();
;     float m_run = -1e30f, l_run = 0.f;
;     uint4 ak0, ak1, ak2, av0, av1, bk0, bk1, bk2, bv0, bv1;
;     const int kr0 = tid / 12, kc0 = tid - kr0 * 12, kr1 = (tid + 512) / 12, kc1 = (tid + 512) - kr1 * 12, kr2 = (tid + 1024) / 12, kc2 = (tid + 1024) - kr2 * 12;
;     const int vr0 = tid >> 4, vr1 = (tid + 512) >> 4, vc = tid & 15;
.LBB0_794:
	s_or_b64 exec, exec, s[26:27]
	s_waitcnt vmcnt(0)
	v_lshlrev_b32_e32 v27, 16, v23
	v_lshlrev_b32_e32 v26, 16, v19
	v_pk_mul_f32 v[26:27], v[26:27], s[48:49] op_sel_hi:[1,0]
	v_lshlrev_b32_e32 v47, 16, v22
	v_pk_mul_f32 v[28:29], v[26:27], v[30:31] op_sel:[0,1] op_sel_hi:[1,0]
	v_pk_mul_f32 v[26:27], v[26:27], v[30:31]
	v_and_b32_e32 v30, 0xffff0000, v19
	v_lshlrev_b32_e32 v46, 16, v18
	v_and_b32_e32 v19, 0xffff0000, v22
	v_and_b32_e32 v18, 0xffff0000, v18
	v_and_b32_e32 v31, 0xffff0000, v23
	v_pk_mul_f32 v[46:47], v[46:47], s[48:49] op_sel_hi:[1,0]
	v_pk_mul_f32 v[22:23], v[18:19], s[48:49] op_sel_hi:[1,0]
	v_pk_mul_f32 v[48:49], v[46:47], v[42:43] op_sel:[0,1] op_sel_hi:[1,0]
	v_pk_mul_f32 v[42:43], v[46:47], v[42:43]
	v_pk_mul_f32 v[18:19], v[22:23], v[40:41] op_sel:[0,1] op_sel_hi:[1,0]
	v_pk_mul_f32 v[22:23], v[22:23], v[40:41]
	v_mov_b32_e32 v40, v42
	v_mov_b32_e32 v41, v22
	v_mov_b32_e32 v22, v43
	v_pk_add_f32 v[22:23], v[40:41], v[22:23]
	v_lshlrev_b32_e32 v41, 16, v21
	v_lshlrev_b32_e32 v40, 16, v17
	v_pk_mul_f32 v[40:41], v[40:41], s[48:49] op_sel_hi:[1,0]
	v_mov_b32_e32 v46, v48
	v_mov_b32_e32 v47, v18
	v_mov_b32_e32 v18, v49
	v_pk_mul_f32 v[42:43], v[40:41], v[32:33] op_sel:[0,1] op_sel_hi:[1,0]
	v_pk_mul_f32 v[40:41], v[40:41], v[32:33]
	v_and_b32_e32 v33, 0xffff0000, v21
	v_and_b32_e32 v32, 0xffff0000, v17
	v_pk_add_f32 v[18:19], v[46:47], v[18:19] neg_lo:[0,1] neg_hi:[0,1]
	v_pk_mul_f32 v[46:47], v[32:33], s[48:49] op_sel_hi:[1,0]
	v_mov_b32_e32 v48, v42
	v_pk_mul_f32 v[32:33], v[46:47], v[34:35] op_sel:[0,1] op_sel_hi:[1,0]
	v_pk_mul_f32 v[34:35], v[46:47], v[34:35]
	v_mov_b32_e32 v49, v32
	v_mov_b32_e32 v32, v43
	v_mov_b32_e32 v42, v40
	v_mov_b32_e32 v43, v34
	v_mov_b32_e32 v34, v41
	v_lshlrev_b32_e32 v41, 16, v20
	v_lshlrev_b32_e32 v40, 16, v16
	v_and_b32_e32 v17, 0xffff0000, v20
	v_and_b32_e32 v16, 0xffff0000, v16
	v_pk_mul_f32 v[40:41], v[40:41], s[48:49] op_sel_hi:[1,0]
	v_pk_mul_f32 v[20:21], v[16:17], s[48:49] op_sel_hi:[1,0]
	v_pk_add_f32 v[34:35], v[42:43], v[34:35]
	v_pk_mul_f32 v[42:43], v[40:41], v[38:39] op_sel:[0,1] op_sel_hi:[1,0]
	v_pk_mul_f32 v[38:39], v[40:41], v[38:39]
	v_pk_mul_f32 v[16:17], v[20:21], v[36:37] op_sel:[0,1] op_sel_hi:[1,0]
	v_pk_mul_f32 v[20:21], v[20:21], v[36:37]
	v_mov_b32_e32 v36, v38
	v_mov_b32_e32 v37, v20
	v_mov_b32_e32 v20, v39
	v_pk_add_f32 v[20:21], v[36:37], v[20:21]
	v_lshlrev_b32_e32 v36, 16, v12
	v_and_b32_e32 v37, 0xffff0000, v12
	v_lshlrev_b32_e32 v12, 16, v13
	v_and_b32_e32 v13, 0xffff0000, v13
	v_pk_mul_f32 v[12:13], v[12:13], s[48:49] op_sel_hi:[1,0]
	v_lshlrev_b32_e32 v38, 16, v14
	v_cvt_pk_bf16_f32 v65, v12, v13
	v_lshlrev_b32_e32 v12, 16, v8
	v_and_b32_e32 v13, 0xffff0000, v8
	v_lshlrev_b32_e32 v8, 16, v9
	v_and_b32_e32 v9, 0xffff0000, v9
	v_pk_mul_f32 v[8:9], v[8:9], s[48:49] op_sel_hi:[1,0]
	v_and_b32_e32 v39, 0xffff0000, v14
	v_cvt_pk_bf16_f32 v69, v8, v9
	v_lshlrev_b32_e32 v8, 16, v4
	v_and_b32_e32 v9, 0xffff0000, v4
	v_lshlrev_b32_e32 v4, 16, v5
	v_and_b32_e32 v5, 0xffff0000, v5
	v_lshlrev_b32_e32 v14, 16, v15
	v_and_b32_e32 v15, 0xffff0000, v15
	v_pk_mul_f32 v[4:5], v[4:5], s[48:49] op_sel_hi:[1,0]
	s_mov_b32 s16, 0x2aaaaaab
	v_pk_mul_f32 v[14:15], v[14:15], s[48:49] op_sel_hi:[1,0]
	v_cvt_pk_bf16_f32 v73, v4, v5
	v_mul_hi_i32 v4, v160, s16
	v_cvt_pk_bf16_f32 v67, v14, v15
	v_lshlrev_b32_e32 v14, 16, v10
	v_and_b32_e32 v15, 0xffff0000, v10
	v_lshlrev_b32_e32 v10, 16, v11
	v_and_b32_e32 v11, 0xffff0000, v11
	v_lshrrev_b32_e32 v5, 31, v4
	v_ashrrev_i32_e32 v4, 1, v4
	v_pk_mul_f32 v[10:11], v[10:11], s[48:49] op_sel_hi:[1,0]
	v_add_u32_e32 v45, v4, v5
	v_cvt_pk_bf16_f32 v71, v10, v11
	v_lshlrev_b32_e32 v10, 16, v6
	v_and_b32_e32 v11, 0xffff0000, v6
	v_lshlrev_b32_e32 v6, 16, v7
	v_and_b32_e32 v7, 0xffff0000, v7
	v_mad_u64_u32 v[4:5], s[38:39], v45, -12, v[160:161]
	v_add_u32_e32 v164, 0x200, v160
	v_pk_mul_f32 v[6:7], v[6:7], s[48:49] op_sel_hi:[1,0]
	v_mul_hi_i32 v5, v164, s16
	v_cvt_pk_bf16_f32 v75, v6, v7
	v_lshrrev_b32_e32 v6, 31, v5
	v_ashrrev_i32_e32 v5, 1, v5
	s_mul_i32 s15, s4, 0xcc000
	v_add_u32_e32 v5, v5, v6
	v_pk_mul_f32 v[38:39], v[38:39], s[48:49] op_sel_hi:[1,0]
	v_pk_mul_f32 v[14:15], v[14:15], s[48:49] op_sel_hi:[1,0]
	s_mul_hi_i32 s5, s4, 0xcc000
	s_add_u32 s26, s90, s15
	v_mad_u64_u32 v[6:7], s[38:39], v5, -12, v[164:165]
	v_add_u32_e32 v162, 0x400, v160
	v_cvt_pk_bf16_f32 v66, v38, v39
	v_cvt_pk_bf16_f32 v70, v14, v15
	v_pk_mul_f32 v[8:9], v[8:9], s[48:49] op_sel_hi:[1,0]
	v_pk_mul_f32 v[10:11], v[10:11], s[48:49] op_sel_hi:[1,0]
	s_addc_u32 s27, s91, s5
	v_mul_hi_i32 v7, v162, s16
	v_lshlrev_b32_e32 v14, 3, v4
	v_lshlrev_b32_e32 v38, 3, v6
	v_pk_mul_f32 v[36:37], v[36:37], s[48:49] op_sel_hi:[1,0]
	v_pk_mul_f32 v[12:13], v[12:13], s[48:49] op_sel_hi:[1,0]
	v_cvt_pk_bf16_f32 v72, v8, v9
	v_cvt_pk_bf16_f32 v74, v10, v11
	v_lshrrev_b32_e32 v8, 31, v7
	v_ashrrev_i32_e32 v7, 1, v7
	v_mov_b64_e32 v[10:11], s[26:27]
	v_ashrrev_i32_e32 v15, 31, v14
	v_ashrrev_i32_e32 v39, 31, v38
	v_cvt_pk_bf16_f32 v64, v36, v37
	v_cvt_pk_bf16_f32 v68, v12, v13
	v_add_u32_e32 v7, v7, v8
	v_mad_i64_i32 v[12:13], s[26:27], v45, s17, v[10:11]
	v_lshlrev_b64 v[14:15], 1, v[14:15]
	v_mad_i64_i32 v[36:37], s[26:27], v5, s17, v[10:11]
	v_lshlrev_b64 v[38:39], 1, v[38:39]
	v_mad_u64_u32 v[8:9], s[38:39], v7, -12, v[162:163]
	v_lshl_add_u64 v[12:13], v[12:13], 0, v[14:15]
	v_lshl_add_u64 v[36:37], v[36:37], 0, v[38:39]
	s_barrier
; DI float bflo(unsigned u) { return __uint_as_float(u << 16); }
; DI float bfhi(unsigned u) { return __uint_as_float(u & 0xffff0000u); }
; DI f32x16 zero16() { f32x16 z; for (int i = 0; i < 16; ++i) z[i] = 0.f; return z; }
; DI void phase_attn(const Params& p, int hf, bool skipctx, char* smem, int& rot) {
;     ...
;       const unsigned a1[4] = {qu[4].x, qu[4].y, qu[4].z, qu[4].w}, a2[4] = {qu[5].x, qu[5].y, qu[5].z, qu[5].w};
;       float o1[8], o2[8];
;       const int sq_ = s0 + w * 32 + r;
; #pragma unroll
;       for (int e = 0; e < 8; ++e) {
;         const float x1 = ((e & 1) ? bfhi(a1[e >> 1]) : bflo(a1[e >> 1])) * QSCALE;
;         const float x2 = ((e & 1) ? bfhi(a2[e >> 1]) : bflo(a2[e >> 1])) * QSCALE;
;         float cs = 1.f, sn = 0.f;
;         if (sq_ >= LC) { cs = axc[(sq_ - LC) * 16 + 8 * h + e]; sn = axs[(sq_ - LC) * 16 + 8 * h + e]; }
;         o1[e] = x1 * cs - x2 * sn; o2[e] = x1 * sn + x2 * cs;
;       }
;       qf[4] = pack8(o1[0], o1[1], o1[2], o1[3], o1[4], o1[5], o1[6], o1[7]);
;       qf[5] = pack8(o2[0], o2[1], o2[2], o2[3], o2[4], o2[5], o2[6], o2[7]);
;     }
;     const bf16_t* Kg = Kb + (size_t)(bl * 8 + head) * S * 96;
;     const bf16_t* Vg = VTb + (size_t)(bl * 8 + head) * 64 * S;
;     f32x16 o[2]; o[0] = zero16(); o[1] = zero16();
;     float m_run = -1e30f, l_run = 0.f;
;     uint4 ak0, ak1, ak2, av0, av1, bk0, bk1, bk2, bv0, bv1;
;     const int kr0 = tid / 12, kc0 = tid - kr0 * 12, kr1 = (tid + 512) / 12, kc1 = (tid + 512) - kr1 * 12, kr2 = (tid + 1024) / 12, kc2 = (tid + 1024) - kr2 * 12;
;     const int vr0 = tid >> 4, vr1 = (tid + 512) >> 4, vc = tid & 15;
;     ...
;     ATT_LOAD(ak0, ak1, ak2, av0, av1, 0);
;     ATT_LOAD(bk0, bk1, bk2, bv0, bv1, 1);
	global_load_dwordx4 v[76:79], v[12:13], off
	global_load_dwordx4 v[80:83], v[36:37], off
	v_lshlrev_b32_e32 v36, 3, v8
	s_mul_i32 s15, s4, 0x88000
	v_readlane_b32 s36, v252, 5
	v_ashrrev_i32_e32 v37, 31, v36
	s_mul_hi_i32 s5, s4, 0x88000
	v_readlane_b32 s37, v252, 6
	s_add_u32 s36, s36, s15
	v_mad_i64_i32 v[12:13], s[26:27], v7, s17, v[10:11]
	v_lshlrev_b64 v[36:37], 1, v[36:37]
	s_addc_u32 s37, s37, s5
	v_lshl_add_u64 v[12:13], v[12:13], 0, v[36:37]
	v_mov_b32_e32 v40, v42
	v_mov_b32_e32 v41, v16
	v_mov_b32_e32 v16, v43
	v_ashrrev_i32_e32 v9, 4, v160
	v_ashrrev_i32_e32 v50, 4, v164
	global_load_dwordx4 v[84:87], v[12:13], off
	v_mov_b64_e32 v[12:13], s[36:37]
	s_movk_i32 s16, 0x2200
	v_lshlrev_b32_e32 v165, 4, v160
	v_cvt_pk_bf16_f32 v100, v20, v21
	v_add_u32_e32 v20, 0x80, v5
	v_pk_add_f32 v[16:17], v[40:41], v[16:17] neg_lo:[0,1] neg_hi:[0,1]
	v_mad_i64_i32 v[40:41], s[26:27], v9, s16, v[12:13]
	v_and_b32_e32 v42, 0xf0, v165
	v_mov_b32_e32 v43, v221
	v_mad_i64_i32 v[12:13], s[26:27], v50, s16, v[12:13]
	v_cvt_pk_bf16_f32 v98, v18, v19
	v_cvt_pk_bf16_f32 v102, v22, v23
	v_add_u32_e32 v18, 0x80, v45
	v_mad_i64_i32 v[20:21], s[26:27], v20, s17, v[10:11]
	v_add_u32_e32 v22, 0x80, v7
	v_lshl_add_u64 v[40:41], v[40:41], 0, v[42:43]
	v_lshl_add_u64 v[12:13], v[12:13], 0, v[42:43]
	v_mad_i64_i32 v[18:19], s[26:27], v18, s17, v[10:11]
	v_lshl_add_u64 v[20:21], v[20:21], 0, v[38:39]
	v_mad_i64_i32 v[10:11], s[26:27], v22, s17, v[10:11]
	global_load_dwordx4 v[92:95], v[40:41], off
	global_load_dwordx4 v[104:107], v[12:13], off
	v_lshl_add_u64 v[18:19], v[18:19], 0, v[14:15]
	v_lshl_add_u64 v[10:11], v[10:11], 0, v[36:37]
	global_load_dwordx4 v[108:111], v[20:21], off
	global_load_dwordx4 v[116:119], v[10:11], off
	global_load_dwordx4 v[120:123], v[40:41], off offset:256
	global_load_dwordx4 v[112:115], v[18:19], off
	global_load_dwordx4 v[124:127], v[12:13], off offset:256
	v_lshlrev_b32_e32 v46, 16, v0
	v_and_b32_e32 v47, 0xffff0000, v0
	v_lshlrev_b32_e32 v0, 16, v1
	v_and_b32_e32 v1, 0xffff0000, v1
	v_pk_mul_f32 v[30:31], v[30:31], s[48:49] op_sel_hi:[1,0]
	v_pk_add_f32 v[32:33], v[48:49], v[32:33] neg_lo:[0,1] neg_hi:[0,1]
	v_pk_mul_f32 v[0:1], v[0:1], s[48:49] op_sel_hi:[1,0]
	v_lshlrev_b32_e32 v48, 16, v2
	v_and_b32_e32 v49, 0xffff0000, v2
	v_lshlrev_b32_e32 v2, 16, v3
	v_and_b32_e32 v3, 0xffff0000, v3
	v_pk_mul_f32 v[2:3], v[2:3], s[48:49] op_sel_hi:[1,0]
	v_cvt_pk_bf16_f32 v89, v0, v1
	v_pk_mul_f32 v[0:1], v[30:31], v[24:25] op_sel:[0,1] op_sel_hi:[1,0]
	v_cvt_pk_bf16_f32 v91, v2, v3
	v_mov_b32_e32 v2, v28
	v_mov_b32_e32 v3, v0
	v_mov_b32_e32 v0, v29
	v_pk_add_f32 v[0:1], v[2:3], v[0:1] neg_lo:[0,1] neg_hi:[0,1]
	v_pk_mul_f32 v[2:3], v[30:31], v[24:25]
	v_mul_lo_u32 v10, v45, s97
	v_mov_b32_e32 v24, v26
	v_mov_b32_e32 v25, v2
	v_mov_b32_e32 v2, v27
	v_add_u32_e32 v10, 0, v10
	v_lshlrev_b32_e32 v4, 4, v4
	v_pk_add_f32 v[2:3], v[24:25], v[2:3]
	v_add_u32_e32 v176, v10, v4
	v_mul_lo_u32 v4, v5, s97
	v_cvt_pk_bf16_f32 v103, v2, v3
	v_mad_i64_i32 v[2:3], s[26:27], v5, s17, 0
	v_add_u32_e32 v4, 0, v4
	v_lshlrev_b32_e32 v5, 4, v6
	v_add_u32_e32 v177, v4, v5
	v_mul_lo_u32 v4, v7, s97
	v_add_u32_e32 v4, 0, v4
	v_lshlrev_b32_e32 v5, 4, v8
	s_movk_i32 s20, 0x108
	v_cvt_pk_bf16_f32 v96, v16, v17
	v_cvt_pk_bf16_f32 v99, v0, v1
	v_mad_i64_i32 v[0:1], s[26:27], v45, s17, 0
	v_mad_i64_i32 v[16:17], s[26:27], v7, s17, 0
	v_add_u32_e32 v178, v4, v5
	v_mul_lo_u32 v4, v9, s20
	v_add_u32_e32 v5, 0, v4
	s_movk_i32 s26, 0x6800
	v_add3_u32 v179, v5, v42, s26
	v_mul_lo_u32 v5, v50, s20
	v_add_u32_e32 v6, 0, v5
	v_add3_u32 v180, v6, v42, s26
	v_or_b32_e32 v181, 32, v161
	v_or_b32_e32 v182, 64, v161
	v_or_b32_e32 v183, 0x60, v161
	v_readlane_b32 s26, v254, 35
	v_mul_u32_u24_e32 v19, 0x108, v44
	v_mad_u32_u24 v18, v44, s97, 0
	v_add_u32_e32 v21, s26, v4
	v_add_u32_e32 v22, s26, v5
	v_add_u32_e32 v23, s26, v161
	v_add_u32_e32 v24, s26, v181
	v_mov_b32_e32 v4, s26
	v_add_u32_e32 v25, s26, v182
	v_add_u32_e32 v26, s26, v183
	v_readlane_b32 s26, v254, 36
	v_mad_u32_u24 v184, v44, s20, v4
	v_add_u32_e32 v20, 0, v161
	v_add_u32_e32 v27, s26, v161
	v_add_u32_e32 v28, s26, v181
	v_mov_b32_e32 v4, s26
	v_add_u32_e32 v29, s26, v182
	v_add_u32_e32 v30, s26, v183
	s_add_u32 s26, s15, 0x1a49c300
	s_addc_u32 s27, s5, 0
	v_mad_u32_u24 v185, v44, s20, v4
	v_mov_b64_e32 v[4:5], s[26:27]
	v_mad_i64_i32 v[166:167], s[26:27], v9, s16, v[4:5]
	v_mad_i64_i32 v[168:169], s[26:27], v50, s16, v[4:5]
	v_mad_i64_i32 v[4:5], s[26:27], s4, v231, v[16:17]
	v_mad_i64_i32 v[2:3], s[26:27], s4, v231, v[2:3]
	v_mad_i64_i32 v[0:1], s[4:5], s4, v231, v[0:1]
	v_lshl_add_u64 v[174:175], v[0:1], 0, v[14:15]
	v_mov_b32_e32 v14, v221
	v_mov_b32_e32 v15, v221
	v_add_u32_e32 v186, v21, v42
	v_add_u32_e32 v187, v22, v42
	v_add_u32_e32 v188, v23, v19
	v_add_u32_e32 v16, v24, v19
	v_add_u32_e32 v17, v25, v19
	v_add_u32_e32 v21, v26, v19
	v_add_u32_e32 v22, v28, v19
	v_add_u32_e32 v23, v29, v19
	v_add_u32_e32 v24, v30, v19
	v_pk_mul_f32 v[46:47], v[46:47], s[48:49] op_sel_hi:[1,0]
	v_pk_mul_f32 v[48:49], v[48:49], s[48:49] op_sel_hi:[1,0]
	v_lshl_add_u64 v[170:171], v[4:5], 0, v[36:37]
	v_lshl_add_u64 v[172:173], v[2:3], 0, v[38:39]
	v_mov_b32_e32 v0, v221
	v_mov_b32_e32 v1, v221
	v_mov_b32_e32 v2, v221
	v_mov_b32_e32 v3, v221
	v_mov_b32_e32 v4, v221
	v_mov_b32_e32 v5, v221
	v_mov_b32_e32 v6, v221
	v_mov_b32_e32 v7, v221
	v_mov_b32_e32 v8, v221
	v_mov_b32_e32 v9, v221
	v_mov_b32_e32 v10, v221
	v_mov_b32_e32 v11, v221
	v_mov_b32_e32 v12, v221
	v_mov_b32_e32 v13, v221
	v_add_u32_e32 v189, v27, v19
	v_add_u32_e32 v190, v18, v220
	v_add_u32_e32 v191, v20, v19
	v_add_u32_e32 v194, 0x2000, v16
	v_add_u32_e32 v204, 0x2000, v17
	v_add_u32_e32 v206, 0x2000, v21
	v_add_u32_e32 v208, 0x2000, v22
	v_add_u32_e32 v210, 0x2000, v23
	v_add_u32_e32 v211, 0x2000, v24
	v_mov_b64_e32 v[30:31], v[14:15]
	v_cvt_pk_bf16_f32 v88, v46, v47
	v_cvt_pk_bf16_f32 v90, v48, v49
	v_cvt_pk_bf16_f32 v97, v32, v33
	v_cvt_pk_bf16_f32 v101, v34, v35
	v_or_b32_e32 v166, v166, v42
	v_or_b32_e32 v168, v168, v42
	s_mov_b32 s4, 0
	v_mov_b32_e32 v212, 0xf149f2ca
	v_mov_b32_e32 v213, 0
	v_mov_b64_e32 v[28:29], v[12:13]
	v_mov_b64_e32 v[26:27], v[10:11]
	v_mov_b64_e32 v[24:25], v[8:9]
	v_mov_b64_e32 v[22:23], v[6:7]
	v_mov_b64_e32 v[20:21], v[4:5]
	v_mov_b64_e32 v[18:19], v[2:3]
	v_mov_b64_e32 v[16:17], v[0:1]
	v_and_b32_e32 v200, 15, v192
	v_lshrrev_b32_e32 v201, 4, v192
	v_mul_u32_u24_e32 v179, 0x110, v201
	v_lshrrev_b32_e32 v202, 1, v200
	v_lshl_add_u32 v179, v202, 5, v179
	v_and_b32_e32 v202, 1, v200
	v_lshl_add_u32 v179, v202, 3, v179
	v_add_u32_e32 v179, 0x6800, v179
	v_add_u32_e32 v180, 0x2200, v179
	v_add_u32_e32 v186, 0xac00, v179
	v_add_u32_e32 v187, 0xac00, v180
	v_and_b32_e32 v200, 31, v192
	v_bfe_u32 v201, v192, 5, 1
	v_mul_u32_u24_e32 v191, 0x110, v200
	v_lshl_add_u32 v191, v201, 4, v191
	v_add_u32_e32 v191, 0x6800, v191
	s_waitcnt vmcnt(9)
; DI void phase_attn(const Params& p, int hf, bool skipctx, char* smem, int& rot) {
;     ...
;       {
;         bf16x8 kf[2][6];
; #pragma unroll
;         for (int kb = 0; kb < 2; ++kb)
; #pragma unroll
;           for (int ks = 0; ks < 6; ++ks) kf[kb][ks] = *(const bf16x8*)(sk + (kb * 32 + r) * KROW + (ks * 16 + h * 8) * 2);
;         __builtin_amdgcn_sched_barrier(0);
; #pragma unroll
;         for (int ks = 0; ks < 6; ++ks)
; #pragma unroll
;           for (int kb = 0; kb < 2; ++kb) st[kb] = MFMA(kf[kb][ks], qf[ks], st[kb]);
;         __builtin_amdgcn_sched_barrier(0);
;       }
;       bf16x8 vf[2][2][2];
; #pragma unroll
;       for (int kb = 0; kb < 2; ++kb)
; #pragma unroll
;         for (int s2 = 0; s2 < 2; ++s2)
; #pragma unroll
;           for (int dvb = 0; dvb < 2; ++dvb) {
;             const char* vp = sv + (dvb * 32 + r) * VROW + (kb * 32 + 16 * s2 + 4 * h) * 2;
;             const s16x4 lo = *(const s16x4*)vp, hi = *(const s16x4*)(vp + 16);
;             vf[kb][s2][dvb] = __builtin_shufflevector(lo, hi, 0, 1, 2, 3, 4, 5, 6, 7);
;           }
;       float mx = st[0][0];
; #pragma unroll
;       for (int i = 0; i < 16; ++i) { mx = fmaxf(mx, st[0][i]); mx = fmaxf(mx, st[1][i]); }
;       if (__any(mx > m_run + 8.f)) {
;         mx = fmaxf(mx, __shfl_xor(mx, 32));
;         const float m_new = fmaxf(m_run, mx);
;         const float alpha = fexp2(m_run - m_new);
;         m_run = m_new;
;         l_run *= alpha;
; #pragma unroll
;         for (int i = 0; i < 16; ++i) { o[0][i] *= alpha; o[1][i] *= alpha; }
;       }
;       float ps = 0.f;
; #pragma unroll
;       for (int kb = 0; kb < 2; ++kb)
; #pragma unroll
;         for (int i = 0; i < 16; ++i) { const float e = fexp2(st[kb][i] - m_run); st[kb][i] = e; ps += e; }
;       l_run += ps;
; #pragma unroll
;       for (int kb = 0; kb < 2; ++kb)
; #pragma unroll
;         for (int s2 = 0; s2 < 2; ++s2) {
;           const bf16x8 pb = pack8(st[kb][8 * s2 + 0], st[kb][8 * s2 + 1], st[kb][8 * s2 + 2], st[kb][8 * s2 + 3], st[kb][8 * s2 + 4], st[kb][8 * s2 + 5], st[kb][8 * s2 + 6], st[kb][8 * s2 + 7]);
; #pragma unroll
;           for (int dvb = 0; dvb < 2; ++dvb) o[dvb] = MFMA(vf[kb][s2][dvb], pb, o[dvb]);
;     ...
;     for (int kt = 0; kt < nkt; kt += 2) {
;       if (kt + 2 < nkt) ATT_LOAD(ak0, ak1, ak2, av0, av1, kt + 2);
;       compute(0, 0); compute(0, 1);
;       ATT_WRITE(bk0, bk1, bk2, bv0, bv1, 1);
	ds_write_b128 v176, v[76:79]
	s_waitcnt vmcnt(8)
	ds_write_b128 v177, v[80:83]
	s_waitcnt vmcnt(7)
	ds_write_b128 v178, v[84:87]
	s_waitcnt vmcnt(6)
	ds_write_b64 v179, v[92:93] offset:0
	ds_write_b64 v179, v[94:95] offset:16
	s_waitcnt vmcnt(5)
	ds_write_b64 v179, v[104:105] offset:8704
	ds_write_b64 v179, v[106:107] offset:8720
	s_waitcnt lgkmcnt(0)
	s_barrier
	v_mov_b32_e32 v194, v176
	v_mov_b32_e32 v204, v177
	v_mov_b32_e32 v206, v178
	v_mov_b32_e32 v208, v179
	v_mov_b32_e32 v210, v190
	v_mov_b32_e32 v211, v191
	v_mov_b32_e32 v220, 0xf149f2ca
	v_mov_b32_e32 v176, 0
	v_mov_b32_e32 v177, 0
	v_mov_b32_e32 v178, 0
	v_mov_b32_e32 v179, 0
	v_mov_b32_e32 v180, 0
	v_mov_b32_e32 v181, 0
	v_mov_b32_e32 v182, 0
	v_mov_b32_e32 v183, 0
	v_mov_b32_e32 v184, 0
	v_mov_b32_e32 v185, 0
	v_mov_b32_e32 v186, 0
	v_mov_b32_e32 v187, 0
	v_mov_b32_e32 v188, 0
	v_mov_b32_e32 v189, 0
	v_mov_b32_e32 v190, 0
	v_mov_b32_e32 v191, 0
	v_mov_b32_e32 v32, 0
	v_mov_b32_e32 v33, 0
	v_mov_b32_e32 v34, 0
	v_mov_b32_e32 v35, 0
	v_mov_b32_e32 v36, 0
	v_mov_b32_e32 v37, 0
	v_mov_b32_e32 v38, 0
	v_mov_b32_e32 v39, 0
	v_mov_b32_e32 v48, 0
	v_mov_b32_e32 v49, 0
	v_mov_b32_e32 v50, 0
	v_mov_b32_e32 v51, 0
	v_mov_b32_e32 v52, 0
	v_mov_b32_e32 v53, 0
	v_mov_b32_e32 v54, 0
	v_mov_b32_e32 v55, 0
	v_mov_b32_e32 v128, 0
	v_mov_b32_e32 v129, 0
	v_mov_b32_e32 v130, 0
	v_mov_b32_e32 v131, 0
	v_mov_b32_e32 v132, 0
	v_mov_b32_e32 v133, 0
	v_mov_b32_e32 v134, 0
	v_mov_b32_e32 v135, 0
	v_mov_b32_e32 v136, 0
	v_mov_b32_e32 v137, 0
	v_mov_b32_e32 v138, 0
	v_mov_b32_e32 v139, 0
	v_mov_b32_e32 v140, 0
	v_mov_b32_e32 v141, 0
	v_mov_b32_e32 v142, 0
	v_mov_b32_e32 v143, 0
	v_mov_b32_e32 v144, 0
	v_mov_b32_e32 v145, 0
	v_mov_b32_e32 v146, 0
	v_mov_b32_e32 v147, 0
	v_mov_b32_e32 v148, 0
	v_mov_b32_e32 v149, 0
	v_mov_b32_e32 v150, 0
	v_mov_b32_e32 v151, 0
	v_mov_b32_e32 v152, 0
	v_mov_b32_e32 v153, 0
	v_mov_b32_e32 v154, 0
	v_mov_b32_e32 v155, 0
	v_mov_b32_e32 v156, 0
	v_mov_b32_e32 v157, 0
	v_mov_b32_e32 v158, 0
	v_mov_b32_e32 v159, 0
	ds_read_b128 v[214:217], v210 offset:0
	ds_read_b128 v[234:237], v210 offset:32
	ds_read_b128 v[238:241], v210 offset:64
	ds_read_b128 v[242:245], v210 offset:96
	ds_read_b128 v[40:43], v210 offset:128
	ds_read_b128 v[44:47], v210 offset:160
	s_cmp_eq_u32 s100, 0
	s_cbranch_scc1 .Lpq0_eb
	s_barrier
.Lpq0_eb:
.LBB0_795:
	s_add_i32 s15, s4, 2
	s_cmp_lt_u32 s15, s13
	s_cselect_b64 s[36:37], -1, 0
	s_cmp_ge_u32 s15, s13
	s_cselect_b64 s[26:27], -1, 0
	s_and_b64 vcc, exec, s[26:27]
	s_cbranch_vccnz .Lpq0_la
	v_lshl_add_u64 v[200:201], s[94:95], 0, v[174:175]
	v_add_co_u32_e32 v200, vcc, 0x18b28000, v200
	v_lshl_add_u64 v[202:203], s[94:95], 0, v[172:173]
	s_nop 0
	v_addc_co_u32_e32 v201, vcc, 0, v201, vcc
	v_add_co_u32_e32 v202, vcc, 0x18b28000, v202
	s_nop 1
	v_addc_co_u32_e32 v203, vcc, 0, v203, vcc
	global_load_dwordx4 v[76:79], v[200:201], off
	global_load_dwordx4 v[80:83], v[202:203], off
	v_lshl_add_u64 v[200:201], s[94:95], 0, v[170:171]
	v_add_co_u32_e32 v200, vcc, 0x18b28000, v200
	v_lshl_add_u64 v[202:203], s[94:95], 0, v[166:167]
	s_nop 0
	v_addc_co_u32_e32 v201, vcc, 0, v201, vcc
	global_load_dwordx4 v[84:87], v[200:201], off
	global_load_dwordx4 v[92:95], v[202:203], off offset:-256
	v_lshl_add_u64 v[200:201], s[94:95], 0, v[168:169]
	global_load_dwordx4 v[104:107], v[200:201], off offset:-256
.Lpq0_la:
	s_waitcnt lgkmcnt(13)
	v_mfma_f32_32x32x16_bf16 v[16:31], v[128:131], v[48:51], v[16:31]
	ds_read_b128 v[128:131], v210 offset:6656
	s_waitcnt lgkmcnt(13)
	v_mfma_f32_32x32x16_bf16 v[0:15], v[132:135], v[48:51], v[0:15]
	ds_read_b128 v[132:135], v210 offset:6688
	s_waitcnt lgkmcnt(13)
	v_mfma_f32_32x32x16_bf16 v[16:31], v[136:139], v[52:55], v[16:31]
	ds_read_b128 v[136:139], v210 offset:6720
	s_waitcnt lgkmcnt(13)
	v_mfma_f32_32x32x16_bf16 v[0:15], v[140:143], v[52:55], v[0:15]
	ds_read_b128 v[140:143], v210 offset:6752
	s_waitcnt lgkmcnt(13)
	v_mfma_f32_32x32x16_bf16 v[16:31], v[144:147], v[32:35], v[16:31]
	ds_read_b128 v[144:147], v210 offset:6784
	s_waitcnt lgkmcnt(13)
	v_mfma_f32_32x32x16_bf16 v[0:15], v[148:151], v[32:35], v[0:15]
	ds_read_b128 v[148:151], v210 offset:6816
	s_waitcnt lgkmcnt(13)
	v_mfma_f32_32x32x16_bf16 v[16:31], v[152:155], v[36:39], v[16:31]
	s_waitcnt lgkmcnt(12)
	v_mfma_f32_32x32x16_bf16 v[0:15], v[156:159], v[36:39], v[0:15]
	s_waitcnt lgkmcnt(11)
	v_mfma_f32_32x32x16_bf16 v[48:63], v[214:217], v[64:67], v[176:191]
	s_waitcnt lgkmcnt(10)
	v_mfma_f32_32x32x16_bf16 v[48:63], v[234:237], v[68:71], v[48:63]
	s_waitcnt lgkmcnt(9)
	v_mfma_f32_32x32x16_bf16 v[48:63], v[238:241], v[72:75], v[48:63]
	s_waitcnt lgkmcnt(8)
	v_mfma_f32_32x32x16_bf16 v[48:63], v[242:245], v[88:91], v[48:63]
	s_waitcnt lgkmcnt(7)
	v_mfma_f32_32x32x16_bf16 v[48:63], v[40:43], v[96:99], v[48:63]
	s_waitcnt lgkmcnt(6)
	v_mfma_f32_32x32x16_bf16 v[48:63], v[44:47], v[100:103], v[48:63]
	s_waitcnt lgkmcnt(5)
	v_mfma_f32_32x32x16_bf16 v[32:47], v[128:131], v[64:67], v[176:191]
	s_waitcnt lgkmcnt(4)
	v_mfma_f32_32x32x16_bf16 v[32:47], v[132:135], v[68:71], v[32:47]
	s_waitcnt lgkmcnt(3)
	v_mfma_f32_32x32x16_bf16 v[32:47], v[136:139], v[72:75], v[32:47]
	s_waitcnt lgkmcnt(2)
	v_mfma_f32_32x32x16_bf16 v[32:47], v[140:143], v[88:91], v[32:47]
	s_waitcnt lgkmcnt(1)
	v_mfma_f32_32x32x16_bf16 v[32:47], v[144:147], v[96:99], v[32:47]
	s_waitcnt lgkmcnt(0)
	v_mfma_f32_32x32x16_bf16 v[32:47], v[148:151], v[100:103], v[32:47]
	s_barrier
	ds_read_b128 v[128:131], v211 offset:0
	ds_read_b128 v[132:135], v211 offset:8704
	ds_read_b128 v[136:139], v211 offset:32
	ds_read_b128 v[140:143], v211 offset:8736
	ds_read_b128 v[144:147], v211 offset:64
	ds_read_b128 v[148:151], v211 offset:8768
	ds_read_b128 v[152:155], v211 offset:96
	ds_read_b128 v[156:159], v211 offset:8800
	s_nop 3
	s_and_b64 vcc, exec, s[26:27]
	s_cbranch_vccnz .Lpq0_wl
	s_waitcnt vmcnt(5)
	s_branch .Lpq0_wg

; DI float fexp2(float x) { return __builtin_amdgcn_exp2f(x); }
; DI void phase_attn(const Params& p, int hf, bool skipctx, char* smem, int& rot) {
;     ...
;       float mx = st[0][0];
; #pragma unroll
;       for (int i = 0; i < 16; ++i) { mx = fmaxf(mx, st[0][i]); mx = fmaxf(mx, st[1][i]); }
;       if (__any(mx > m_run + 8.f)) {
;         mx = fmaxf(mx, __shfl_xor(mx, 32));
;         const float m_new = fmaxf(m_run, mx);
;         const float alpha = fexp2(m_run - m_new);
;         m_run = m_new;
;         l_run *= alpha;
; #pragma unroll
;         for (int i = 0; i < 16; ++i) { o[0][i] *= alpha; o[1][i] *= alpha; }
;       }
;       float ps = 0.f;
; #pragma unroll
;       for (int kb = 0; kb < 2; ++kb)
; #pragma unroll
;         for (int i = 0; i < 16; ++i) { const float e = fexp2(st[kb][i] - m_run); st[kb][i] = e; ps += e; }
;       l_run += ps;
; #pragma unroll
;       for (int kb = 0; kb < 2; ++kb)
; #pragma unroll
;         for (int s2 = 0; s2 < 2; ++s2) {
;           const bf16x8 pb = pack8(st[kb][8 * s2 + 0], st[kb][8 * s2 + 1], st[kb][8 * s2 + 2], st[kb][8 * s2 + 3], st[kb][8 * s2 + 4], st[kb][8 * s2 + 5], st[kb][8 * s2 + 6], st[kb][8 * s2 + 7]);
;     ...
;       ATT_WRITE(bk0, bk1, bk2, bv0, bv1, 1);
.Lpq0_wg:
	ds_write_b128 v194, v[112:115] offset:44032
	ds_write_b128 v204, v[108:111] offset:44032
	ds_write_b128 v206, v[116:119] offset:44032
	ds_write_b64 v208, v[120:121] offset:44032
	ds_write_b64 v208, v[122:123] offset:44048
	ds_write_b64 v208, v[124:125] offset:52736
	ds_write_b64 v208, v[126:127] offset:52752
	v_max3_f32 v195, v48, v49, v50
	v_max3_f32 v200, v32, v33, v34
	v_max3_f32 v195, v195, v51, v52
	v_max3_f32 v200, v200, v35, v36
	v_max3_f32 v195, v195, v53, v54
	v_max3_f32 v200, v200, v37, v38
	v_max3_f32 v195, v195, v55, v56
	v_max3_f32 v200, v200, v39, v40
	v_max3_f32 v195, v195, v57, v58
	v_max3_f32 v200, v200, v41, v42
	v_max3_f32 v195, v195, v59, v60
	v_max3_f32 v200, v200, v43, v44
	v_max3_f32 v195, v195, v61, v62
	v_max3_f32 v200, v200, v45, v46
	v_max3_f32 v195, v195, v63, v47
	v_max_f32_e32 v195, v195, v200
	v_cmp_gt_f32_e32 vcc, v195, v220
	s_cbranch_vccz .Lpq0_s0_n
	v_sub_f32_e32 v195, v195, v176
	v_cmp_lt_i32_e32 vcc, v224, v207
	s_nop 1
	v_cndmask_b32_e32 v200, v205, v224, vcc
	v_lshlrev_b32_e32 v200, 2, v200
	ds_bpermute_b32 v200, v200, v195
	s_waitcnt lgkmcnt(0)
	v_max3_f32 v195, v212, v195, v200
	v_sub_f32_e32 v200, v212, v195
	v_exp_f32_e32 v200, v200
	v_mov_b32_e32 v212, v195
	v_add_f32_e32 v202, v195, v176
	v_mul_f32_e32 v213, v213, v200
	v_pk_mul_f32 v[30:31], v[30:31], v[200:201] op_sel_hi:[1,0]
	v_pk_mul_f32 v[28:29], v[28:29], v[200:201] op_sel_hi:[1,0]
	v_pk_mul_f32 v[26:27], v[26:27], v[200:201] op_sel_hi:[1,0]
	v_pk_mul_f32 v[24:25], v[24:25], v[200:201] op_sel_hi:[1,0]
	v_pk_mul_f32 v[22:23], v[22:23], v[200:201] op_sel_hi:[1,0]
	v_pk_mul_f32 v[20:21], v[20:21], v[200:201] op_sel_hi:[1,0]
	v_pk_mul_f32 v[18:19], v[18:19], v[200:201] op_sel_hi:[1,0]
	v_pk_mul_f32 v[16:17], v[16:17], v[200:201] op_sel_hi:[1,0]
	v_pk_mul_f32 v[14:15], v[14:15], v[200:201] op_sel_hi:[1,0]
	v_pk_mul_f32 v[12:13], v[12:13], v[200:201] op_sel_hi:[1,0]
	v_pk_mul_f32 v[10:11], v[10:11], v[200:201] op_sel_hi:[1,0]
	v_pk_mul_f32 v[8:9], v[8:9], v[200:201] op_sel_hi:[1,0]
	v_pk_mul_f32 v[6:7], v[6:7], v[200:201] op_sel_hi:[1,0]
	v_pk_mul_f32 v[4:5], v[4:5], v[200:201] op_sel_hi:[1,0]
	v_pk_mul_f32 v[2:3], v[2:3], v[200:201] op_sel_hi:[1,0]
	v_pk_mul_f32 v[0:1], v[0:1], v[200:201] op_sel_hi:[1,0]
	v_sub_f32_e32 v32, v32, v202
	v_sub_f32_e32 v33, v33, v202
	v_sub_f32_e32 v34, v34, v202
	v_sub_f32_e32 v35, v35, v202
	v_sub_f32_e32 v36, v36, v202
	v_sub_f32_e32 v37, v37, v202
	v_sub_f32_e32 v38, v38, v202
	v_sub_f32_e32 v39, v39, v202
	v_sub_f32_e32 v40, v40, v202
	v_sub_f32_e32 v41, v41, v202
	v_sub_f32_e32 v42, v42, v202
	v_sub_f32_e32 v43, v43, v202
	v_sub_f32_e32 v44, v44, v202
	v_sub_f32_e32 v45, v45, v202
	v_sub_f32_e32 v46, v46, v202
	v_sub_f32_e32 v47, v47, v202
	v_sub_f32_e32 v48, v48, v202
	v_sub_f32_e32 v49, v49, v202
	v_sub_f32_e32 v50, v50, v202
	v_sub_f32_e32 v51, v51, v202
	v_sub_f32_e32 v52, v52, v202
	v_sub_f32_e32 v53, v53, v202
	v_sub_f32_e32 v54, v54, v202
	v_sub_f32_e32 v55, v55, v202
	v_sub_f32_e32 v56, v56, v202
	v_sub_f32_e32 v57, v57, v202
	v_sub_f32_e32 v58, v58, v202
	v_sub_f32_e32 v59, v59, v202
	v_sub_f32_e32 v60, v60, v202
	v_sub_f32_e32 v61, v61, v202
	v_sub_f32_e32 v62, v62, v202
	v_sub_f32_e32 v63, v63, v202
	v_sub_f32_e32 v176, 0, v195
	v_sub_f32_e32 v177, 0, v195
	v_sub_f32_e32 v178, 0, v195
	v_sub_f32_e32 v179, 0, v195
	v_sub_f32_e32 v180, 0, v195
	v_sub_f32_e32 v181, 0, v195
	v_sub_f32_e32 v182, 0, v195
	v_sub_f32_e32 v183, 0, v195
	v_sub_f32_e32 v184, 0, v195
	v_sub_f32_e32 v185, 0, v195
	v_sub_f32_e32 v186, 0, v195
	v_sub_f32_e32 v187, 0, v195
	v_sub_f32_e32 v188, 0, v195
	v_sub_f32_e32 v189, 0, v195
	v_sub_f32_e32 v190, 0, v195
	v_sub_f32_e32 v191, 0, v195
	v_mov_b32_e32 v220, 0x41000000
.Lpq0_s0_n:
	v_exp_f32_e32 v48, v48
	v_exp_f32_e32 v49, v49
	v_exp_f32_e32 v50, v50
	v_exp_f32_e32 v51, v51
	v_exp_f32_e32 v52, v52
	v_exp_f32_e32 v53, v53
	v_exp_f32_e32 v54, v54
	v_exp_f32_e32 v55, v55
	v_exp_f32_e32 v56, v56
	v_exp_f32_e32 v57, v57
	v_exp_f32_e32 v58, v58
	v_exp_f32_e32 v59, v59
	v_exp_f32_e32 v60, v60
	v_exp_f32_e32 v61, v61
	v_exp_f32_e32 v62, v62
	v_exp_f32_e32 v63, v63
	v_add_f32_e32 v201, v48, v49
	v_add_f32_e32 v201, v201, v50
	v_add_f32_e32 v201, v201, v51
	v_add_f32_e32 v201, v201, v52
	v_add_f32_e32 v201, v201, v53
	v_add_f32_e32 v201, v201, v54
	v_add_f32_e32 v201, v201, v55
	v_add_f32_e32 v201, v201, v56
	v_add_f32_e32 v201, v201, v57
	v_add_f32_e32 v201, v201, v58
	v_add_f32_e32 v201, v201, v59
	v_add_f32_e32 v201, v201, v60
	v_add_f32_e32 v201, v201, v61
	v_add_f32_e32 v201, v201, v62
	v_add_f32_e32 v201, v201, v63
	v_cvt_pk_bf16_f32 v48, v48, v49
	v_cvt_pk_bf16_f32 v49, v50, v51
	v_cvt_pk_bf16_f32 v50, v52, v53
	v_cvt_pk_bf16_f32 v51, v54, v55
	v_cvt_pk_bf16_f32 v52, v56, v57
	v_cvt_pk_bf16_f32 v53, v58, v59
	v_cvt_pk_bf16_f32 v54, v60, v61
	v_cvt_pk_bf16_f32 v55, v62, v63
	v_exp_f32_e32 v32, v32
	v_exp_f32_e32 v33, v33
	v_exp_f32_e32 v34, v34
	v_exp_f32_e32 v35, v35
	v_exp_f32_e32 v36, v36
	v_exp_f32_e32 v37, v37
	v_exp_f32_e32 v38, v38
	v_exp_f32_e32 v39, v39
	v_exp_f32_e32 v40, v40
	v_exp_f32_e32 v41, v41
	v_exp_f32_e32 v42, v42
	v_exp_f32_e32 v43, v43
	v_exp_f32_e32 v44, v44
	v_exp_f32_e32 v45, v45
	v_exp_f32_e32 v46, v46
	v_exp_f32_e32 v47, v47
	v_add_f32_e32 v201, v201, v32
	v_add_f32_e32 v201, v201, v33
	v_add_f32_e32 v201, v201, v34
	v_add_f32_e32 v201, v201, v35
	v_add_f32_e32 v201, v201, v36
	v_add_f32_e32 v201, v201, v37
	v_add_f32_e32 v201, v201, v38
	v_add_f32_e32 v201, v201, v39
	v_add_f32_e32 v201, v201, v40
	v_add_f32_e32 v201, v201, v41
	v_add_f32_e32 v201, v201, v42
	v_add_f32_e32 v201, v201, v43
	v_add_f32_e32 v201, v201, v44
	v_add_f32_e32 v201, v201, v45
	v_add_f32_e32 v201, v201, v46
	v_add_f32_e32 v201, v201, v47
	v_cvt_pk_bf16_f32 v32, v32, v33
	v_cvt_pk_bf16_f32 v33, v34, v35
	v_cvt_pk_bf16_f32 v34, v36, v37
	v_cvt_pk_bf16_f32 v35, v38, v39
	v_cvt_pk_bf16_f32 v36, v40, v41
	v_cvt_pk_bf16_f32 v37, v42, v43
	v_cvt_pk_bf16_f32 v38, v44, v45
	v_cvt_pk_bf16_f32 v39, v46, v47
	v_add_f32_e32 v213, v213, v201
	ds_read_b128 v[214:217], v210 offset:13312
	ds_read_b128 v[234:237], v210 offset:13344
	ds_read_b128 v[238:241], v210 offset:13376
	ds_read_b128 v[242:245], v210 offset:13408
	ds_read_b128 v[40:43], v210 offset:13440
	ds_read_b128 v[44:47], v210 offset:13472
	s_waitcnt lgkmcnt(6)
	s_barrier
; #define MFMA(a, b, c) __builtin_amdgcn_mfma_f32_32x32x16_bf16((a), (b), (c), 0, 0, 0)
; DI float fexp2(float x) { return __builtin_amdgcn_exp2f(x); }
; DI void phase_attn(const Params& p, int hf, bool skipctx, char* smem, int& rot) {
;     ...
;       {
;         bf16x8 kf[2][6];
; #pragma unroll
;         for (int kb = 0; kb < 2; ++kb)
; #pragma unroll
;           for (int ks = 0; ks < 6; ++ks) kf[kb][ks] = *(const bf16x8*)(sk + (kb * 32 + r) * KROW + (ks * 16 + h * 8) * 2);
;         __builtin_amdgcn_sched_barrier(0);
; #pragma unroll
;         for (int ks = 0; ks < 6; ++ks)
; #pragma unroll
;           for (int kb = 0; kb < 2; ++kb) st[kb] = MFMA(kf[kb][ks], qf[ks], st[kb]);
;         __builtin_amdgcn_sched_barrier(0);
;       }
;       bf16x8 vf[2][2][2];
; #pragma unroll
;       for (int kb = 0; kb < 2; ++kb)
; #pragma unroll
;         for (int s2 = 0; s2 < 2; ++s2)
; #pragma unroll
;           for (int dvb = 0; dvb < 2; ++dvb) {
;             const char* vp = sv + (dvb * 32 + r) * VROW + (kb * 32 + 16 * s2 + 4 * h) * 2;
;             const s16x4 lo = *(const s16x4*)vp, hi = *(const s16x4*)(vp + 16);
;             vf[kb][s2][dvb] = __builtin_shufflevector(lo, hi, 0, 1, 2, 3, 4, 5, 6, 7);
;           }
;       float mx = st[0][0];
; #pragma unroll
;       for (int i = 0; i < 16; ++i) { mx = fmaxf(mx, st[0][i]); mx = fmaxf(mx, st[1][i]); }
;       if (__any(mx > m_run + 8.f)) {
;         mx = fmaxf(mx, __shfl_xor(mx, 32));
;         const float m_new = fmaxf(m_run, mx);
;         const float alpha = fexp2(m_run - m_new);
;         m_run = m_new;
;         l_run *= alpha;
; #pragma unroll
;         for (int i = 0; i < 16; ++i) { o[0][i] *= alpha; o[1][i] *= alpha; }
;       }
;     ...
;       compute(0, 0); compute(0, 1);
	s_waitcnt lgkmcnt(13)
	v_mfma_f32_32x32x16_bf16 v[16:31], v[128:131], v[48:51], v[16:31]
	ds_read_b128 v[128:131], v210 offset:19968
	s_waitcnt lgkmcnt(13)
	v_mfma_f32_32x32x16_bf16 v[0:15], v[132:135], v[48:51], v[0:15]
	ds_read_b128 v[132:135], v210 offset:20000
	s_waitcnt lgkmcnt(13)
	v_mfma_f32_32x32x16_bf16 v[16:31], v[136:139], v[52:55], v[16:31]
	ds_read_b128 v[136:139], v210 offset:20032
	s_waitcnt lgkmcnt(13)
	v_mfma_f32_32x32x16_bf16 v[0:15], v[140:143], v[52:55], v[0:15]
	ds_read_b128 v[140:143], v210 offset:20064
	s_waitcnt lgkmcnt(13)
	v_mfma_f32_32x32x16_bf16 v[16:31], v[144:147], v[32:35], v[16:31]
	ds_read_b128 v[144:147], v210 offset:20096
	s_waitcnt lgkmcnt(13)
	v_mfma_f32_32x32x16_bf16 v[0:15], v[148:151], v[32:35], v[0:15]
	ds_read_b128 v[148:151], v210 offset:20128
	s_waitcnt lgkmcnt(13)
	v_mfma_f32_32x32x16_bf16 v[16:31], v[152:155], v[36:39], v[16:31]
	s_waitcnt lgkmcnt(12)
	v_mfma_f32_32x32x16_bf16 v[0:15], v[156:159], v[36:39], v[0:15]
	s_waitcnt lgkmcnt(11)
	v_mfma_f32_32x32x16_bf16 v[48:63], v[214:217], v[64:67], v[176:191]
	s_waitcnt lgkmcnt(10)
	v_mfma_f32_32x32x16_bf16 v[48:63], v[234:237], v[68:71], v[48:63]
	s_waitcnt lgkmcnt(9)
	v_mfma_f32_32x32x16_bf16 v[48:63], v[238:241], v[72:75], v[48:63]
	s_waitcnt lgkmcnt(8)
	v_mfma_f32_32x32x16_bf16 v[48:63], v[242:245], v[88:91], v[48:63]
	s_waitcnt lgkmcnt(7)
	v_mfma_f32_32x32x16_bf16 v[48:63], v[40:43], v[96:99], v[48:63]
	s_waitcnt lgkmcnt(6)
	v_mfma_f32_32x32x16_bf16 v[48:63], v[44:47], v[100:103], v[48:63]
	s_waitcnt lgkmcnt(5)
	v_mfma_f32_32x32x16_bf16 v[32:47], v[128:131], v[64:67], v[176:191]
	s_waitcnt lgkmcnt(4)
	v_mfma_f32_32x32x16_bf16 v[32:47], v[132:135], v[68:71], v[32:47]
	s_waitcnt lgkmcnt(3)
	v_mfma_f32_32x32x16_bf16 v[32:47], v[136:139], v[72:75], v[32:47]
	s_waitcnt lgkmcnt(2)
	v_mfma_f32_32x32x16_bf16 v[32:47], v[140:143], v[88:91], v[32:47]
	s_waitcnt lgkmcnt(1)
	v_mfma_f32_32x32x16_bf16 v[32:47], v[144:147], v[96:99], v[32:47]
	s_waitcnt lgkmcnt(0)
	v_mfma_f32_32x32x16_bf16 v[32:47], v[148:151], v[100:103], v[32:47]
	s_barrier
	ds_read_b128 v[128:131], v211 offset:128
	ds_read_b128 v[132:135], v211 offset:8832
	ds_read_b128 v[136:139], v211 offset:160
	ds_read_b128 v[140:143], v211 offset:8864
	ds_read_b128 v[144:147], v211 offset:192
	ds_read_b128 v[148:151], v211 offset:8896
	ds_read_b128 v[152:155], v211 offset:224
	ds_read_b128 v[156:159], v211 offset:8928
	s_nop 3
	v_max3_f32 v195, v48, v49, v50
	v_max3_f32 v200, v32, v33, v34
	v_max3_f32 v195, v195, v51, v52
	v_max3_f32 v200, v200, v35, v36
	v_max3_f32 v195, v195, v53, v54
	v_max3_f32 v200, v200, v37, v38
	v_max3_f32 v195, v195, v55, v56
	v_max3_f32 v200, v200, v39, v40
	v_max3_f32 v195, v195, v57, v58
	v_max3_f32 v200, v200, v41, v42
	v_max3_f32 v195, v195, v59, v60
	v_max3_f32 v200, v200, v43, v44
	v_max3_f32 v195, v195, v61, v62
	v_max3_f32 v200, v200, v45, v46
	v_max3_f32 v195, v195, v63, v47
	v_max_f32_e32 v195, v195, v200
	v_cmp_gt_f32_e32 vcc, v195, v220
	s_cbranch_vccz .Lpq0_s1_n
	v_sub_f32_e32 v195, v195, v176
	v_cmp_lt_i32_e32 vcc, v224, v207
	s_nop 1
	v_cndmask_b32_e32 v200, v205, v224, vcc
	v_lshlrev_b32_e32 v200, 2, v200
	ds_bpermute_b32 v200, v200, v195
	s_waitcnt lgkmcnt(0)
	v_max3_f32 v195, v212, v195, v200
	v_sub_f32_e32 v200, v212, v195
	v_exp_f32_e32 v200, v200
	v_mov_b32_e32 v212, v195
	v_add_f32_e32 v202, v195, v176
	v_mul_f32_e32 v213, v213, v200
	v_pk_mul_f32 v[30:31], v[30:31], v[200:201] op_sel_hi:[1,0]
	v_pk_mul_f32 v[28:29], v[28:29], v[200:201] op_sel_hi:[1,0]
	v_pk_mul_f32 v[26:27], v[26:27], v[200:201] op_sel_hi:[1,0]
	v_pk_mul_f32 v[24:25], v[24:25], v[200:201] op_sel_hi:[1,0]
	v_pk_mul_f32 v[22:23], v[22:23], v[200:201] op_sel_hi:[1,0]
	v_pk_mul_f32 v[20:21], v[20:21], v[200:201] op_sel_hi:[1,0]
	v_pk_mul_f32 v[18:19], v[18:19], v[200:201] op_sel_hi:[1,0]
	v_pk_mul_f32 v[16:17], v[16:17], v[200:201] op_sel_hi:[1,0]
	v_pk_mul_f32 v[14:15], v[14:15], v[200:201] op_sel_hi:[1,0]
	v_pk_mul_f32 v[12:13], v[12:13], v[200:201] op_sel_hi:[1,0]
	v_pk_mul_f32 v[10:11], v[10:11], v[200:201] op_sel_hi:[1,0]
	v_pk_mul_f32 v[8:9], v[8:9], v[200:201] op_sel_hi:[1,0]
	v_pk_mul_f32 v[6:7], v[6:7], v[200:201] op_sel_hi:[1,0]
	v_pk_mul_f32 v[4:5], v[4:5], v[200:201] op_sel_hi:[1,0]
	v_pk_mul_f32 v[2:3], v[2:3], v[200:201] op_sel_hi:[1,0]
	v_pk_mul_f32 v[0:1], v[0:1], v[200:201] op_sel_hi:[1,0]
	v_sub_f32_e32 v32, v32, v202
	v_sub_f32_e32 v33, v33, v202
	v_sub_f32_e32 v34, v34, v202
	v_sub_f32_e32 v35, v35, v202
	v_sub_f32_e32 v36, v36, v202
	v_sub_f32_e32 v37, v37, v202
	v_sub_f32_e32 v38, v38, v202
	v_sub_f32_e32 v39, v39, v202
	v_sub_f32_e32 v40, v40, v202
	v_sub_f32_e32 v41, v41, v202
	v_sub_f32_e32 v42, v42, v202
	v_sub_f32_e32 v43, v43, v202
	v_sub_f32_e32 v44, v44, v202
	v_sub_f32_e32 v45, v45, v202
	v_sub_f32_e32 v46, v46, v202
	v_sub_f32_e32 v47, v47, v202
	v_sub_f32_e32 v48, v48, v202
	v_sub_f32_e32 v49, v49, v202
	v_sub_f32_e32 v50, v50, v202
	v_sub_f32_e32 v51, v51, v202
	v_sub_f32_e32 v52, v52, v202
	v_sub_f32_e32 v53, v53, v202
	v_sub_f32_e32 v54, v54, v202
	v_sub_f32_e32 v55, v55, v202
	v_sub_f32_e32 v56, v56, v202
	v_sub_f32_e32 v57, v57, v202
	v_sub_f32_e32 v58, v58, v202
	v_sub_f32_e32 v59, v59, v202
	v_sub_f32_e32 v60, v60, v202
	v_sub_f32_e32 v61, v61, v202
	v_sub_f32_e32 v62, v62, v202
	v_sub_f32_e32 v63, v63, v202
	v_sub_f32_e32 v176, 0, v195
	v_sub_f32_e32 v177, 0, v195
	v_sub_f32_e32 v178, 0, v195
	v_sub_f32_e32 v179, 0, v195
	v_sub_f32_e32 v180, 0, v195
	v_sub_f32_e32 v181, 0, v195
	v_sub_f32_e32 v182, 0, v195
	v_sub_f32_e32 v183, 0, v195
	v_sub_f32_e32 v184, 0, v195
	v_sub_f32_e32 v185, 0, v195
	v_sub_f32_e32 v186, 0, v195
	v_sub_f32_e32 v187, 0, v195
	v_sub_f32_e32 v188, 0, v195
	v_sub_f32_e32 v189, 0, v195
	v_sub_f32_e32 v190, 0, v195
	v_sub_f32_e32 v191, 0, v195
	v_mov_b32_e32 v220, 0x41000000
; #define MFMA(a, b, c) __builtin_amdgcn_mfma_f32_32x32x16_bf16((a), (b), (c), 0, 0, 0)
; DI float fexp2(float x) { return __builtin_amdgcn_exp2f(x); }
; DI void phase_attn(const Params& p, int hf, bool skipctx, char* smem, int& rot) {
;     ...
;       {
;         bf16x8 kf[2][6];
; #pragma unroll
;         for (int kb = 0; kb < 2; ++kb)
; #pragma unroll
;           for (int ks = 0; ks < 6; ++ks) kf[kb][ks] = *(const bf16x8*)(sk + (kb * 32 + r) * KROW + (ks * 16 + h * 8) * 2);
;         __builtin_amdgcn_sched_barrier(0);
; #pragma unroll
;         for (int ks = 0; ks < 6; ++ks)
; #pragma unroll
;           for (int kb = 0; kb < 2; ++kb) st[kb] = MFMA(kf[kb][ks], qf[ks], st[kb]);
;         __builtin_amdgcn_sched_barrier(0);
;     ...
;       float ps = 0.f;
; #pragma unroll
;       for (int kb = 0; kb < 2; ++kb)
; #pragma unroll
;         for (int i = 0; i < 16; ++i) { const float e = fexp2(st[kb][i] - m_run); st[kb][i] = e; ps += e; }
;       l_run += ps;
; #pragma unroll
;       for (int kb = 0; kb < 2; ++kb)
; #pragma unroll
;         for (int s2 = 0; s2 < 2; ++s2) {
;           const bf16x8 pb = pack8(st[kb][8 * s2 + 0], st[kb][8 * s2 + 1], st[kb][8 * s2 + 2], st[kb][8 * s2 + 3], st[kb][8 * s2 + 4], st[kb][8 * s2 + 5], st[kb][8 * s2 + 6], st[kb][8 * s2 + 7]);
;     ...
;       if (kt + 3 < nkt) ATT_LOAD(bk0, bk1, bk2, bv0, bv1, kt + 3);
;       compute(1, 0); compute(1, 1);
;       if (kt + 2 < nkt) ATT_WRITE(ak0, ak1, ak2, av0, av1, 0);
.Lpq0_s1_n:
	v_exp_f32_e32 v48, v48
	v_exp_f32_e32 v49, v49
	v_exp_f32_e32 v50, v50
	v_exp_f32_e32 v51, v51
	v_exp_f32_e32 v52, v52
	v_exp_f32_e32 v53, v53
	v_exp_f32_e32 v54, v54
	v_exp_f32_e32 v55, v55
	v_exp_f32_e32 v56, v56
	v_exp_f32_e32 v57, v57
	v_exp_f32_e32 v58, v58
	v_exp_f32_e32 v59, v59
	v_exp_f32_e32 v60, v60
	v_exp_f32_e32 v61, v61
	v_exp_f32_e32 v62, v62
	v_exp_f32_e32 v63, v63
	v_add_f32_e32 v201, v48, v49
	v_add_f32_e32 v201, v201, v50
	v_add_f32_e32 v201, v201, v51
	v_add_f32_e32 v201, v201, v52
	v_add_f32_e32 v201, v201, v53
	v_add_f32_e32 v201, v201, v54
	v_add_f32_e32 v201, v201, v55
	v_add_f32_e32 v201, v201, v56
	v_add_f32_e32 v201, v201, v57
	v_add_f32_e32 v201, v201, v58
	v_add_f32_e32 v201, v201, v59
	v_add_f32_e32 v201, v201, v60
	v_add_f32_e32 v201, v201, v61
	v_add_f32_e32 v201, v201, v62
	v_add_f32_e32 v201, v201, v63
	v_cvt_pk_bf16_f32 v48, v48, v49
	v_cvt_pk_bf16_f32 v49, v50, v51
	v_cvt_pk_bf16_f32 v50, v52, v53
	v_cvt_pk_bf16_f32 v51, v54, v55
	v_cvt_pk_bf16_f32 v52, v56, v57
	v_cvt_pk_bf16_f32 v53, v58, v59
	v_cvt_pk_bf16_f32 v54, v60, v61
	v_cvt_pk_bf16_f32 v55, v62, v63
	v_exp_f32_e32 v32, v32
	v_exp_f32_e32 v33, v33
	v_exp_f32_e32 v34, v34
	v_exp_f32_e32 v35, v35
	v_exp_f32_e32 v36, v36
	v_exp_f32_e32 v37, v37
	v_exp_f32_e32 v38, v38
	v_exp_f32_e32 v39, v39
	v_exp_f32_e32 v40, v40
	v_exp_f32_e32 v41, v41
	v_exp_f32_e32 v42, v42
	v_exp_f32_e32 v43, v43
	v_exp_f32_e32 v44, v44
	v_exp_f32_e32 v45, v45
	v_exp_f32_e32 v46, v46
	v_exp_f32_e32 v47, v47
	v_add_f32_e32 v201, v201, v32
	v_add_f32_e32 v201, v201, v33
	v_add_f32_e32 v201, v201, v34
	v_add_f32_e32 v201, v201, v35
	v_add_f32_e32 v201, v201, v36
	v_add_f32_e32 v201, v201, v37
	v_add_f32_e32 v201, v201, v38
	v_add_f32_e32 v201, v201, v39
	v_add_f32_e32 v201, v201, v40
	v_add_f32_e32 v201, v201, v41
	v_add_f32_e32 v201, v201, v42
	v_add_f32_e32 v201, v201, v43
	v_add_f32_e32 v201, v201, v44
	v_add_f32_e32 v201, v201, v45
	v_add_f32_e32 v201, v201, v46
	v_add_f32_e32 v201, v201, v47
	v_cvt_pk_bf16_f32 v32, v32, v33
	v_cvt_pk_bf16_f32 v33, v34, v35
	v_cvt_pk_bf16_f32 v34, v36, v37
	v_cvt_pk_bf16_f32 v35, v38, v39
	v_cvt_pk_bf16_f32 v36, v40, v41
	v_cvt_pk_bf16_f32 v37, v42, v43
	v_cvt_pk_bf16_f32 v38, v44, v45
	v_cvt_pk_bf16_f32 v39, v46, v47
	v_add_f32_e32 v213, v213, v201
	ds_read_b128 v[214:217], v210 offset:44032
	ds_read_b128 v[234:237], v210 offset:44064
	ds_read_b128 v[238:241], v210 offset:44096
	ds_read_b128 v[242:245], v210 offset:44128
	ds_read_b128 v[40:43], v210 offset:44160
	ds_read_b128 v[44:47], v210 offset:44192
	s_barrier
	s_add_i32 s4, s4, 3
	s_cmp_ge_u32 s4, s13
	s_cbranch_scc1 .Lpq0_lb
	v_lshl_add_u64 v[108:109], s[94:95], 0, v[174:175]
	v_add_co_u32_e32 v108, vcc, 0x18b2e000, v108
	v_lshl_add_u64 v[110:111], s[94:95], 0, v[172:173]
	s_nop 0
	v_addc_co_u32_e32 v109, vcc, 0, v109, vcc
	v_add_co_u32_e32 v110, vcc, 0x18b2e000, v110
	v_lshl_add_u64 v[116:117], s[94:95], 0, v[170:171]
	s_nop 0
	v_addc_co_u32_e32 v111, vcc, 0, v111, vcc
	v_add_co_u32_e32 v116, vcc, 0x18b2e000, v116
	v_lshl_add_u64 v[120:121], s[94:95], 0, v[166:167]
	s_nop 0
	v_addc_co_u32_e32 v117, vcc, 0, v117, vcc
	v_lshl_add_u64 v[124:125], s[94:95], 0, v[168:169]
	global_load_dwordx4 v[112:115], v[108:109], off
	s_nop 0
	global_load_dwordx4 v[108:111], v[110:111], off
	s_nop 0
	global_load_dwordx4 v[116:119], v[116:117], off
	s_nop 0
	global_load_dwordx4 v[120:123], v[120:121], off
	s_nop 0
	global_load_dwordx4 v[124:127], v[124:125], off
.Lpq0_lb:
	s_waitcnt lgkmcnt(13)
	v_mfma_f32_32x32x16_bf16 v[16:31], v[128:131], v[48:51], v[16:31]
	ds_read_b128 v[128:131], v210 offset:50688
	s_waitcnt lgkmcnt(13)
	v_mfma_f32_32x32x16_bf16 v[0:15], v[132:135], v[48:51], v[0:15]
	ds_read_b128 v[132:135], v210 offset:50720
	s_waitcnt lgkmcnt(13)
	v_mfma_f32_32x32x16_bf16 v[16:31], v[136:139], v[52:55], v[16:31]
	ds_read_b128 v[136:139], v210 offset:50752
	s_waitcnt lgkmcnt(13)
	v_mfma_f32_32x32x16_bf16 v[0:15], v[140:143], v[52:55], v[0:15]
	ds_read_b128 v[140:143], v210 offset:50784
	s_waitcnt lgkmcnt(13)
	v_mfma_f32_32x32x16_bf16 v[16:31], v[144:147], v[32:35], v[16:31]
	ds_read_b128 v[144:147], v210 offset:50816
	s_waitcnt lgkmcnt(13)
	v_mfma_f32_32x32x16_bf16 v[0:15], v[148:151], v[32:35], v[0:15]
	ds_read_b128 v[148:151], v210 offset:50848
	s_waitcnt lgkmcnt(13)
	v_mfma_f32_32x32x16_bf16 v[16:31], v[152:155], v[36:39], v[16:31]
	s_waitcnt lgkmcnt(12)
	v_mfma_f32_32x32x16_bf16 v[0:15], v[156:159], v[36:39], v[0:15]
	s_waitcnt lgkmcnt(11)
	v_mfma_f32_32x32x16_bf16 v[48:63], v[214:217], v[64:67], v[176:191]
	s_waitcnt lgkmcnt(10)
	v_mfma_f32_32x32x16_bf16 v[48:63], v[234:237], v[68:71], v[48:63]
	s_waitcnt lgkmcnt(9)
	v_mfma_f32_32x32x16_bf16 v[48:63], v[238:241], v[72:75], v[48:63]
	s_waitcnt lgkmcnt(8)
	v_mfma_f32_32x32x16_bf16 v[48:63], v[242:245], v[88:91], v[48:63]
	s_waitcnt lgkmcnt(7)
	v_mfma_f32_32x32x16_bf16 v[48:63], v[40:43], v[96:99], v[48:63]
	s_waitcnt lgkmcnt(6)
	v_mfma_f32_32x32x16_bf16 v[48:63], v[44:47], v[100:103], v[48:63]
	s_waitcnt lgkmcnt(5)
	v_mfma_f32_32x32x16_bf16 v[32:47], v[128:131], v[64:67], v[176:191]
	s_waitcnt lgkmcnt(4)
	v_mfma_f32_32x32x16_bf16 v[32:47], v[132:135], v[68:71], v[32:47]
	s_waitcnt lgkmcnt(3)
	v_mfma_f32_32x32x16_bf16 v[32:47], v[136:139], v[72:75], v[32:47]
	s_waitcnt lgkmcnt(2)
	v_mfma_f32_32x32x16_bf16 v[32:47], v[140:143], v[88:91], v[32:47]
	s_waitcnt lgkmcnt(1)
	v_mfma_f32_32x32x16_bf16 v[32:47], v[144:147], v[96:99], v[32:47]
	s_waitcnt lgkmcnt(0)
	v_mfma_f32_32x32x16_bf16 v[32:47], v[148:151], v[100:103], v[32:47]
	s_barrier
	ds_read_b128 v[128:131], v211 offset:44032
	ds_read_b128 v[132:135], v211 offset:52736
	ds_read_b128 v[136:139], v211 offset:44064
	ds_read_b128 v[140:143], v211 offset:52768
	ds_read_b128 v[144:147], v211 offset:44096
	ds_read_b128 v[148:151], v211 offset:52800
	ds_read_b128 v[152:155], v211 offset:44128
	ds_read_b128 v[156:159], v211 offset:52832
	s_nop 3
	s_andn2_b64 vcc, exec, s[36:37]
	s_cbranch_vccnz .Lpq0_wa
	s_waitcnt vmcnt(5)
	ds_write_b128 v194, v[76:79]
	ds_write_b128 v204, v[80:83]
	ds_write_b128 v206, v[84:87]
	ds_write_b64 v208, v[92:93]
	ds_write_b64 v208, v[94:95] offset:16
	ds_write_b64 v208, v[104:105] offset:8704
	ds_write_b64 v208, v[106:107] offset:8720
; DI float fexp2(float x) { return __builtin_amdgcn_exp2f(x); }
; DI void phase_attn(const Params& p, int hf, bool skipctx, char* smem, int& rot) {
;     ...
;       float mx = st[0][0];
; #pragma unroll
;       for (int i = 0; i < 16; ++i) { mx = fmaxf(mx, st[0][i]); mx = fmaxf(mx, st[1][i]); }
;       if (__any(mx > m_run + 8.f)) {
;         mx = fmaxf(mx, __shfl_xor(mx, 32));
;         const float m_new = fmaxf(m_run, mx);
;         const float alpha = fexp2(m_run - m_new);
;         m_run = m_new;
;         l_run *= alpha;
; #pragma unroll
;         for (int i = 0; i < 16; ++i) { o[0][i] *= alpha; o[1][i] *= alpha; }
;       }
;       float ps = 0.f;
; #pragma unroll
;       for (int kb = 0; kb < 2; ++kb)
; #pragma unroll
;         for (int i = 0; i < 16; ++i) { const float e = fexp2(st[kb][i] - m_run); st[kb][i] = e; ps += e; }
;       l_run += ps;
; #pragma unroll
;       for (int kb = 0; kb < 2; ++kb)
; #pragma unroll
;         for (int s2 = 0; s2 < 2; ++s2) {
;           const bf16x8 pb = pack8(st[kb][8 * s2 + 0], st[kb][8 * s2 + 1], st[kb][8 * s2 + 2], st[kb][8 * s2 + 3], st[kb][8 * s2 + 4], st[kb][8 * s2 + 5], st[kb][8 * s2 + 6], st[kb][8 * s2 + 7]);
.Lpq0_wa:
	v_max3_f32 v195, v48, v49, v50
	v_max3_f32 v200, v32, v33, v34
	v_max3_f32 v195, v195, v51, v52
	v_max3_f32 v200, v200, v35, v36
	v_max3_f32 v195, v195, v53, v54
	v_max3_f32 v200, v200, v37, v38
	v_max3_f32 v195, v195, v55, v56
	v_max3_f32 v200, v200, v39, v40
	v_max3_f32 v195, v195, v57, v58
	v_max3_f32 v200, v200, v41, v42
	v_max3_f32 v195, v195, v59, v60
	v_max3_f32 v200, v200, v43, v44
	v_max3_f32 v195, v195, v61, v62
	v_max3_f32 v200, v200, v45, v46
	v_max3_f32 v195, v195, v63, v47
	v_max_f32_e32 v195, v195, v200
	v_cmp_gt_f32_e32 vcc, v195, v220
	s_cbranch_vccz .Lpq0_s2_n
	v_sub_f32_e32 v195, v195, v176
	v_cmp_lt_i32_e32 vcc, v224, v207
	s_nop 1
	v_cndmask_b32_e32 v200, v205, v224, vcc
	v_lshlrev_b32_e32 v200, 2, v200
	ds_bpermute_b32 v200, v200, v195
	s_waitcnt lgkmcnt(0)
	v_max3_f32 v195, v212, v195, v200
	v_sub_f32_e32 v200, v212, v195
	v_exp_f32_e32 v200, v200
	v_mov_b32_e32 v212, v195
	v_add_f32_e32 v202, v195, v176
	v_mul_f32_e32 v213, v213, v200
	v_pk_mul_f32 v[30:31], v[30:31], v[200:201] op_sel_hi:[1,0]
	v_pk_mul_f32 v[28:29], v[28:29], v[200:201] op_sel_hi:[1,0]
	v_pk_mul_f32 v[26:27], v[26:27], v[200:201] op_sel_hi:[1,0]
	v_pk_mul_f32 v[24:25], v[24:25], v[200:201] op_sel_hi:[1,0]
	v_pk_mul_f32 v[22:23], v[22:23], v[200:201] op_sel_hi:[1,0]
	v_pk_mul_f32 v[20:21], v[20:21], v[200:201] op_sel_hi:[1,0]
	v_pk_mul_f32 v[18:19], v[18:19], v[200:201] op_sel_hi:[1,0]
	v_pk_mul_f32 v[16:17], v[16:17], v[200:201] op_sel_hi:[1,0]
	v_pk_mul_f32 v[14:15], v[14:15], v[200:201] op_sel_hi:[1,0]
	v_pk_mul_f32 v[12:13], v[12:13], v[200:201] op_sel_hi:[1,0]
	v_pk_mul_f32 v[10:11], v[10:11], v[200:201] op_sel_hi:[1,0]
	v_pk_mul_f32 v[8:9], v[8:9], v[200:201] op_sel_hi:[1,0]
	v_pk_mul_f32 v[6:7], v[6:7], v[200:201] op_sel_hi:[1,0]
	v_pk_mul_f32 v[4:5], v[4:5], v[200:201] op_sel_hi:[1,0]
	v_pk_mul_f32 v[2:3], v[2:3], v[200:201] op_sel_hi:[1,0]
	v_pk_mul_f32 v[0:1], v[0:1], v[200:201] op_sel_hi:[1,0]
	v_sub_f32_e32 v32, v32, v202
	v_sub_f32_e32 v33, v33, v202
	v_sub_f32_e32 v34, v34, v202
	v_sub_f32_e32 v35, v35, v202
	v_sub_f32_e32 v36, v36, v202
	v_sub_f32_e32 v37, v37, v202
	v_sub_f32_e32 v38, v38, v202
	v_sub_f32_e32 v39, v39, v202
	v_sub_f32_e32 v40, v40, v202
	v_sub_f32_e32 v41, v41, v202
	v_sub_f32_e32 v42, v42, v202
	v_sub_f32_e32 v43, v43, v202
	v_sub_f32_e32 v44, v44, v202
	v_sub_f32_e32 v45, v45, v202
	v_sub_f32_e32 v46, v46, v202
	v_sub_f32_e32 v47, v47, v202
	v_sub_f32_e32 v48, v48, v202
	v_sub_f32_e32 v49, v49, v202
	v_sub_f32_e32 v50, v50, v202
	v_sub_f32_e32 v51, v51, v202
	v_sub_f32_e32 v52, v52, v202
	v_sub_f32_e32 v53, v53, v202
	v_sub_f32_e32 v54, v54, v202
	v_sub_f32_e32 v55, v55, v202
	v_sub_f32_e32 v56, v56, v202
	v_sub_f32_e32 v57, v57, v202
	v_sub_f32_e32 v58, v58, v202
	v_sub_f32_e32 v59, v59, v202
	v_sub_f32_e32 v60, v60, v202
	v_sub_f32_e32 v61, v61, v202
	v_sub_f32_e32 v62, v62, v202
	v_sub_f32_e32 v63, v63, v202
	v_sub_f32_e32 v176, 0, v195
	v_sub_f32_e32 v177, 0, v195
	v_sub_f32_e32 v178, 0, v195
	v_sub_f32_e32 v179, 0, v195
	v_sub_f32_e32 v180, 0, v195
	v_sub_f32_e32 v181, 0, v195
	v_sub_f32_e32 v182, 0, v195
	v_sub_f32_e32 v183, 0, v195
	v_sub_f32_e32 v184, 0, v195
	v_sub_f32_e32 v185, 0, v195
	v_sub_f32_e32 v186, 0, v195
	v_sub_f32_e32 v187, 0, v195
	v_sub_f32_e32 v188, 0, v195
	v_sub_f32_e32 v189, 0, v195
	v_sub_f32_e32 v190, 0, v195
	v_sub_f32_e32 v191, 0, v195
	v_mov_b32_e32 v220, 0x41000000
.Lpq0_s2_n:
	v_exp_f32_e32 v48, v48
	v_exp_f32_e32 v49, v49
	v_exp_f32_e32 v50, v50
	v_exp_f32_e32 v51, v51
	v_exp_f32_e32 v52, v52
	v_exp_f32_e32 v53, v53
	v_exp_f32_e32 v54, v54
	v_exp_f32_e32 v55, v55
	v_exp_f32_e32 v56, v56
	v_exp_f32_e32 v57, v57
	v_exp_f32_e32 v58, v58
	v_exp_f32_e32 v59, v59
	v_exp_f32_e32 v60, v60
	v_exp_f32_e32 v61, v61
	v_exp_f32_e32 v62, v62
	v_exp_f32_e32 v63, v63
	v_add_f32_e32 v201, v48, v49
	v_add_f32_e32 v201, v201, v50
	v_add_f32_e32 v201, v201, v51
	v_add_f32_e32 v201, v201, v52
	v_add_f32_e32 v201, v201, v53
	v_add_f32_e32 v201, v201, v54
	v_add_f32_e32 v201, v201, v55
	v_add_f32_e32 v201, v201, v56
	v_add_f32_e32 v201, v201, v57
	v_add_f32_e32 v201, v201, v58
	v_add_f32_e32 v201, v201, v59
	v_add_f32_e32 v201, v201, v60
	v_add_f32_e32 v201, v201, v61
	v_add_f32_e32 v201, v201, v62
	v_add_f32_e32 v201, v201, v63
	v_cvt_pk_bf16_f32 v48, v48, v49
	v_cvt_pk_bf16_f32 v49, v50, v51
	v_cvt_pk_bf16_f32 v50, v52, v53
	v_cvt_pk_bf16_f32 v51, v54, v55
	v_cvt_pk_bf16_f32 v52, v56, v57
	v_cvt_pk_bf16_f32 v53, v58, v59
	v_cvt_pk_bf16_f32 v54, v60, v61
	v_cvt_pk_bf16_f32 v55, v62, v63
	v_exp_f32_e32 v32, v32
	v_exp_f32_e32 v33, v33
	v_exp_f32_e32 v34, v34
	v_exp_f32_e32 v35, v35
	v_exp_f32_e32 v36, v36
	v_exp_f32_e32 v37, v37
	v_exp_f32_e32 v38, v38
	v_exp_f32_e32 v39, v39
	v_exp_f32_e32 v40, v40
	v_exp_f32_e32 v41, v41
	v_exp_f32_e32 v42, v42
	v_exp_f32_e32 v43, v43
	v_exp_f32_e32 v44, v44
	v_exp_f32_e32 v45, v45
	v_exp_f32_e32 v46, v46
	v_exp_f32_e32 v47, v47
	v_add_f32_e32 v201, v201, v32
	v_add_f32_e32 v201, v201, v33
	v_add_f32_e32 v201, v201, v34
	v_add_f32_e32 v201, v201, v35
	v_add_f32_e32 v201, v201, v36
	v_add_f32_e32 v201, v201, v37
	v_add_f32_e32 v201, v201, v38
	v_add_f32_e32 v201, v201, v39
	v_add_f32_e32 v201, v201, v40
	v_add_f32_e32 v201, v201, v41
	v_add_f32_e32 v201, v201, v42
	v_add_f32_e32 v201, v201, v43
	v_add_f32_e32 v201, v201, v44
	v_add_f32_e32 v201, v201, v45
	v_add_f32_e32 v201, v201, v46
	v_add_f32_e32 v201, v201, v47
	v_cvt_pk_bf16_f32 v32, v32, v33
	v_cvt_pk_bf16_f32 v33, v34, v35
	v_cvt_pk_bf16_f32 v34, v36, v37
	v_cvt_pk_bf16_f32 v35, v38, v39
	v_cvt_pk_bf16_f32 v36, v40, v41
	v_cvt_pk_bf16_f32 v37, v42, v43
	v_cvt_pk_bf16_f32 v38, v44, v45
	v_cvt_pk_bf16_f32 v39, v46, v47
	v_add_f32_e32 v213, v213, v201
	ds_read_b128 v[214:217], v210 offset:57344
	ds_read_b128 v[234:237], v210 offset:57376
	ds_read_b128 v[238:241], v210 offset:57408
	ds_read_b128 v[242:245], v210 offset:57440
	ds_read_b128 v[40:43], v210 offset:57472
	ds_read_b128 v[44:47], v210 offset:57504
	s_waitcnt lgkmcnt(6)
	s_barrier
; #define MFMA(a, b, c) __builtin_amdgcn_mfma_f32_32x32x16_bf16((a), (b), (c), 0, 0, 0)
; DI float fexp2(float x) { return __builtin_amdgcn_exp2f(x); }
; DI void phase_attn(const Params& p, int hf, bool skipctx, char* smem, int& rot) {
;     ...
;       {
;         bf16x8 kf[2][6];
; #pragma unroll
;         for (int kb = 0; kb < 2; ++kb)
; #pragma unroll
;           for (int ks = 0; ks < 6; ++ks) kf[kb][ks] = *(const bf16x8*)(sk + (kb * 32 + r) * KROW + (ks * 16 + h * 8) * 2);
;         __builtin_amdgcn_sched_barrier(0);
; #pragma unroll
;         for (int ks = 0; ks < 6; ++ks)
; #pragma unroll
;           for (int kb = 0; kb < 2; ++kb) st[kb] = MFMA(kf[kb][ks], qf[ks], st[kb]);
;         __builtin_amdgcn_sched_barrier(0);
;       }
;       bf16x8 vf[2][2][2];
; #pragma unroll
;       for (int kb = 0; kb < 2; ++kb)
; #pragma unroll
;         for (int s2 = 0; s2 < 2; ++s2)
; #pragma unroll
;           for (int dvb = 0; dvb < 2; ++dvb) {
;             const char* vp = sv + (dvb * 32 + r) * VROW + (kb * 32 + 16 * s2 + 4 * h) * 2;
;             const s16x4 lo = *(const s16x4*)vp, hi = *(const s16x4*)(vp + 16);
;             vf[kb][s2][dvb] = __builtin_shufflevector(lo, hi, 0, 1, 2, 3, 4, 5, 6, 7);
;           }
;       float mx = st[0][0];
; #pragma unroll
;       for (int i = 0; i < 16; ++i) { mx = fmaxf(mx, st[0][i]); mx = fmaxf(mx, st[1][i]); }
;       if (__any(mx > m_run + 8.f)) {
;         mx = fmaxf(mx, __shfl_xor(mx, 32));
;         const float m_new = fmaxf(m_run, mx);
;         const float alpha = fexp2(m_run - m_new);
;         m_run = m_new;
;         l_run *= alpha;
; #pragma unroll
;         for (int i = 0; i < 16; ++i) { o[0][i] *= alpha; o[1][i] *= alpha; }
;       }
	s_waitcnt lgkmcnt(13)
	v_mfma_f32_32x32x16_bf16 v[16:31], v[128:131], v[48:51], v[16:31]
	ds_read_b128 v[128:131], v210 offset:64000
	s_waitcnt lgkmcnt(13)
	v_mfma_f32_32x32x16_bf16 v[0:15], v[132:135], v[48:51], v[0:15]
	ds_read_b128 v[132:135], v210 offset:64032
	s_waitcnt lgkmcnt(13)
	v_mfma_f32_32x32x16_bf16 v[16:31], v[136:139], v[52:55], v[16:31]
	ds_read_b128 v[136:139], v210 offset:64064
	s_waitcnt lgkmcnt(13)
	v_mfma_f32_32x32x16_bf16 v[0:15], v[140:143], v[52:55], v[0:15]
	ds_read_b128 v[140:143], v210 offset:64096
	s_waitcnt lgkmcnt(13)
	v_mfma_f32_32x32x16_bf16 v[16:31], v[144:147], v[32:35], v[16:31]
	ds_read_b128 v[144:147], v210 offset:64128
	s_waitcnt lgkmcnt(13)
	v_mfma_f32_32x32x16_bf16 v[0:15], v[148:151], v[32:35], v[0:15]
	ds_read_b128 v[148:151], v210 offset:64160
	s_waitcnt lgkmcnt(13)
	v_mfma_f32_32x32x16_bf16 v[16:31], v[152:155], v[36:39], v[16:31]
	s_waitcnt lgkmcnt(12)
	v_mfma_f32_32x32x16_bf16 v[0:15], v[156:159], v[36:39], v[0:15]
	s_waitcnt lgkmcnt(11)
	v_mfma_f32_32x32x16_bf16 v[48:63], v[214:217], v[64:67], v[176:191]
	s_waitcnt lgkmcnt(10)
	v_mfma_f32_32x32x16_bf16 v[48:63], v[234:237], v[68:71], v[48:63]
	s_waitcnt lgkmcnt(9)
	v_mfma_f32_32x32x16_bf16 v[48:63], v[238:241], v[72:75], v[48:63]
	s_waitcnt lgkmcnt(8)
	v_mfma_f32_32x32x16_bf16 v[48:63], v[242:245], v[88:91], v[48:63]
	s_waitcnt lgkmcnt(7)
	v_mfma_f32_32x32x16_bf16 v[48:63], v[40:43], v[96:99], v[48:63]
	s_waitcnt lgkmcnt(6)
	v_mfma_f32_32x32x16_bf16 v[48:63], v[44:47], v[100:103], v[48:63]
	s_waitcnt lgkmcnt(5)
	v_mfma_f32_32x32x16_bf16 v[32:47], v[128:131], v[64:67], v[176:191]
	s_waitcnt lgkmcnt(4)
	v_mfma_f32_32x32x16_bf16 v[32:47], v[132:135], v[68:71], v[32:47]
	s_waitcnt lgkmcnt(3)
	v_mfma_f32_32x32x16_bf16 v[32:47], v[136:139], v[72:75], v[32:47]
	s_waitcnt lgkmcnt(2)
	v_mfma_f32_32x32x16_bf16 v[32:47], v[140:143], v[88:91], v[32:47]
	s_waitcnt lgkmcnt(1)
	v_mfma_f32_32x32x16_bf16 v[32:47], v[144:147], v[96:99], v[32:47]
	s_waitcnt lgkmcnt(0)
	v_mfma_f32_32x32x16_bf16 v[32:47], v[148:151], v[100:103], v[32:47]
	s_barrier
	ds_read_b128 v[128:131], v211 offset:44160
	ds_read_b128 v[132:135], v211 offset:52864
	ds_read_b128 v[136:139], v211 offset:44192
	ds_read_b128 v[140:143], v211 offset:52896
	ds_read_b128 v[144:147], v211 offset:44224
	ds_read_b128 v[148:151], v211 offset:52928
	ds_read_b128 v[152:155], v211 offset:44256
	ds_read_b128 v[156:159], v211 offset:52960
	s_nop 3
	v_max3_f32 v195, v48, v49, v50
	v_max3_f32 v200, v32, v33, v34
	v_max3_f32 v195, v195, v51, v52
	v_max3_f32 v200, v200, v35, v36
	v_max3_f32 v195, v195, v53, v54
	v_max3_f32 v200, v200, v37, v38
	v_max3_f32 v195, v195, v55, v56
	v_max3_f32 v200, v200, v39, v40
	v_max3_f32 v195, v195, v57, v58
	v_max3_f32 v200, v200, v41, v42
	v_max3_f32 v195, v195, v59, v60
	v_max3_f32 v200, v200, v43, v44
	v_max3_f32 v195, v195, v61, v62
	v_max3_f32 v200, v200, v45, v46
	v_max3_f32 v195, v195, v63, v47
	v_max_f32_e32 v195, v195, v200
	v_cmp_gt_f32_e32 vcc, v195, v220
	s_cbranch_vccz .Lpq0_s3_n
	v_sub_f32_e32 v195, v195, v176
	v_cmp_lt_i32_e32 vcc, v224, v207
	s_nop 1
	v_cndmask_b32_e32 v200, v205, v224, vcc
	v_lshlrev_b32_e32 v200, 2, v200
	ds_bpermute_b32 v200, v200, v195
	s_waitcnt lgkmcnt(0)
	v_max3_f32 v195, v212, v195, v200
	v_sub_f32_e32 v200, v212, v195
	v_exp_f32_e32 v200, v200
	v_mov_b32_e32 v212, v195
	v_add_f32_e32 v202, v195, v176
	v_mul_f32_e32 v213, v213, v200
	v_pk_mul_f32 v[30:31], v[30:31], v[200:201] op_sel_hi:[1,0]
	v_pk_mul_f32 v[28:29], v[28:29], v[200:201] op_sel_hi:[1,0]
	v_pk_mul_f32 v[26:27], v[26:27], v[200:201] op_sel_hi:[1,0]
	v_pk_mul_f32 v[24:25], v[24:25], v[200:201] op_sel_hi:[1,0]
	v_pk_mul_f32 v[22:23], v[22:23], v[200:201] op_sel_hi:[1,0]
	v_pk_mul_f32 v[20:21], v[20:21], v[200:201] op_sel_hi:[1,0]
	v_pk_mul_f32 v[18:19], v[18:19], v[200:201] op_sel_hi:[1,0]
	v_pk_mul_f32 v[16:17], v[16:17], v[200:201] op_sel_hi:[1,0]
	v_pk_mul_f32 v[14:15], v[14:15], v[200:201] op_sel_hi:[1,0]
	v_pk_mul_f32 v[12:13], v[12:13], v[200:201] op_sel_hi:[1,0]
	v_pk_mul_f32 v[10:11], v[10:11], v[200:201] op_sel_hi:[1,0]
	v_pk_mul_f32 v[8:9], v[8:9], v[200:201] op_sel_hi:[1,0]
	v_pk_mul_f32 v[6:7], v[6:7], v[200:201] op_sel_hi:[1,0]
	v_pk_mul_f32 v[4:5], v[4:5], v[200:201] op_sel_hi:[1,0]
	v_pk_mul_f32 v[2:3], v[2:3], v[200:201] op_sel_hi:[1,0]
	v_pk_mul_f32 v[0:1], v[0:1], v[200:201] op_sel_hi:[1,0]
	v_sub_f32_e32 v32, v32, v202
	v_sub_f32_e32 v33, v33, v202
	v_sub_f32_e32 v34, v34, v202
	v_sub_f32_e32 v35, v35, v202
	v_sub_f32_e32 v36, v36, v202
	v_sub_f32_e32 v37, v37, v202
	v_sub_f32_e32 v38, v38, v202
	v_sub_f32_e32 v39, v39, v202
	v_sub_f32_e32 v40, v40, v202
	v_sub_f32_e32 v41, v41, v202
	v_sub_f32_e32 v42, v42, v202
	v_sub_f32_e32 v43, v43, v202
	v_sub_f32_e32 v44, v44, v202
	v_sub_f32_e32 v45, v45, v202
	v_sub_f32_e32 v46, v46, v202
	v_sub_f32_e32 v47, v47, v202
	v_sub_f32_e32 v48, v48, v202
	v_sub_f32_e32 v49, v49, v202
	v_sub_f32_e32 v50, v50, v202
	v_sub_f32_e32 v51, v51, v202
	v_sub_f32_e32 v52, v52, v202
	v_sub_f32_e32 v53, v53, v202
	v_sub_f32_e32 v54, v54, v202
	v_sub_f32_e32 v55, v55, v202
	v_sub_f32_e32 v56, v56, v202
	v_sub_f32_e32 v57, v57, v202
	v_sub_f32_e32 v58, v58, v202
	v_sub_f32_e32 v59, v59, v202
	v_sub_f32_e32 v60, v60, v202
	v_sub_f32_e32 v61, v61, v202
	v_sub_f32_e32 v62, v62, v202
	v_sub_f32_e32 v63, v63, v202
	v_sub_f32_e32 v176, 0, v195
	v_sub_f32_e32 v177, 0, v195
	v_sub_f32_e32 v178, 0, v195
	v_sub_f32_e32 v179, 0, v195
	v_sub_f32_e32 v180, 0, v195
	v_sub_f32_e32 v181, 0, v195
	v_sub_f32_e32 v182, 0, v195
	v_sub_f32_e32 v183, 0, v195
	v_sub_f32_e32 v184, 0, v195
	v_sub_f32_e32 v185, 0, v195
	v_sub_f32_e32 v186, 0, v195
	v_sub_f32_e32 v187, 0, v195
	v_sub_f32_e32 v188, 0, v195
	v_sub_f32_e32 v189, 0, v195
	v_sub_f32_e32 v190, 0, v195
	v_sub_f32_e32 v191, 0, v195
	v_mov_b32_e32 v220, 0x41000000
; DI float fexp2(float x) { return __builtin_amdgcn_exp2f(x); }
; DI void phase_attn(const Params& p, int hf, bool skipctx, char* smem, int& rot) {
;     ...
;       float ps = 0.f;
; #pragma unroll
;       for (int kb = 0; kb < 2; ++kb)
; #pragma unroll
;         for (int i = 0; i < 16; ++i) { const float e = fexp2(st[kb][i] - m_run); st[kb][i] = e; ps += e; }
;       l_run += ps;
; #pragma unroll
;       for (int kb = 0; kb < 2; ++kb)
; #pragma unroll
;         for (int s2 = 0; s2 < 2; ++s2) {
;           const bf16x8 pb = pack8(st[kb][8 * s2 + 0], st[kb][8 * s2 + 1], st[kb][8 * s2 + 2], st[kb][8 * s2 + 3], st[kb][8 * s2 + 4], st[kb][8 * s2 + 5], st[kb][8 * s2 + 6], st[kb][8 * s2 + 7]);
;     ...
;     for (int kt = 0; kt < nkt; kt += 2) {
;       if (kt + 2 < nkt) ATT_LOAD(ak0, ak1, ak2, av0, av1, kt + 2);
;       compute(0, 0); compute(0, 1);
;       ATT_WRITE(bk0, bk1, bk2, bv0, bv1, 1);
;       __syncthreads();
;       if (kt + 3 < nkt) ATT_LOAD(bk0, bk1, bk2, bv0, bv1, kt + 3);
;       compute(1, 0); compute(1, 1);
;       if (kt + 2 < nkt) ATT_WRITE(ak0, ak1, ak2, av0, av1, 0);
;       __syncthreads();
;     }
.Lpq0_s3_n:
	v_exp_f32_e32 v48, v48
	v_exp_f32_e32 v49, v49
	v_exp_f32_e32 v50, v50
	v_exp_f32_e32 v51, v51
	v_exp_f32_e32 v52, v52
	v_exp_f32_e32 v53, v53
	v_exp_f32_e32 v54, v54
	v_exp_f32_e32 v55, v55
	v_exp_f32_e32 v56, v56
	v_exp_f32_e32 v57, v57
	v_exp_f32_e32 v58, v58
	v_exp_f32_e32 v59, v59
	v_exp_f32_e32 v60, v60
	v_exp_f32_e32 v61, v61
	v_exp_f32_e32 v62, v62
	v_exp_f32_e32 v63, v63
	v_add_f32_e32 v201, v48, v49
	v_add_f32_e32 v201, v201, v50
	v_add_f32_e32 v201, v201, v51
	v_add_f32_e32 v201, v201, v52
	v_add_f32_e32 v201, v201, v53
	v_add_f32_e32 v201, v201, v54
	v_add_f32_e32 v201, v201, v55
	v_add_f32_e32 v201, v201, v56
	v_add_f32_e32 v201, v201, v57
	v_add_f32_e32 v201, v201, v58
	v_add_f32_e32 v201, v201, v59
	v_add_f32_e32 v201, v201, v60
	v_add_f32_e32 v201, v201, v61
	v_add_f32_e32 v201, v201, v62
	v_add_f32_e32 v201, v201, v63
	v_cvt_pk_bf16_f32 v48, v48, v49
	v_cvt_pk_bf16_f32 v49, v50, v51
	v_cvt_pk_bf16_f32 v50, v52, v53
	v_cvt_pk_bf16_f32 v51, v54, v55
	v_cvt_pk_bf16_f32 v52, v56, v57
	v_cvt_pk_bf16_f32 v53, v58, v59
	v_cvt_pk_bf16_f32 v54, v60, v61
	v_cvt_pk_bf16_f32 v55, v62, v63
	v_exp_f32_e32 v32, v32
	v_exp_f32_e32 v33, v33
	v_exp_f32_e32 v34, v34
	v_exp_f32_e32 v35, v35
	v_exp_f32_e32 v36, v36
	v_exp_f32_e32 v37, v37
	v_exp_f32_e32 v38, v38
	v_exp_f32_e32 v39, v39
	v_exp_f32_e32 v40, v40
	v_exp_f32_e32 v41, v41
	v_exp_f32_e32 v42, v42
	v_exp_f32_e32 v43, v43
	v_exp_f32_e32 v44, v44
	v_exp_f32_e32 v45, v45
	v_exp_f32_e32 v46, v46
	v_exp_f32_e32 v47, v47
	v_add_f32_e32 v201, v201, v32
	v_add_f32_e32 v201, v201, v33
	v_add_f32_e32 v201, v201, v34
	v_add_f32_e32 v201, v201, v35
	v_add_f32_e32 v201, v201, v36
	v_add_f32_e32 v201, v201, v37
	v_add_f32_e32 v201, v201, v38
	v_add_f32_e32 v201, v201, v39
	v_add_f32_e32 v201, v201, v40
	v_add_f32_e32 v201, v201, v41
	v_add_f32_e32 v201, v201, v42
	v_add_f32_e32 v201, v201, v43
	v_add_f32_e32 v201, v201, v44
	v_add_f32_e32 v201, v201, v45
	v_add_f32_e32 v201, v201, v46
	v_add_f32_e32 v201, v201, v47
	v_cvt_pk_bf16_f32 v32, v32, v33
	v_cvt_pk_bf16_f32 v33, v34, v35
	v_cvt_pk_bf16_f32 v34, v36, v37
	v_cvt_pk_bf16_f32 v35, v38, v39
	v_cvt_pk_bf16_f32 v36, v40, v41
	v_cvt_pk_bf16_f32 v37, v42, v43
	v_cvt_pk_bf16_f32 v38, v44, v45
	v_cvt_pk_bf16_f32 v39, v46, v47
	v_add_f32_e32 v213, v213, v201
	v_lshl_add_u64 v[166:167], v[166:167], 0, s[24:25]
	v_lshl_add_u64 v[168:169], v[168:169], 0, s[24:25]
	v_lshl_add_u64 v[170:171], v[170:171], 0, s[30:31]
	v_lshl_add_u64 v[172:173], v[172:173], 0, s[30:31]
	v_lshl_add_u64 v[174:175], v[174:175], 0, s[30:31]
	ds_read_b128 v[214:217], v210 offset:0
	ds_read_b128 v[234:237], v210 offset:32
	ds_read_b128 v[238:241], v210 offset:64
	ds_read_b128 v[242:245], v210 offset:96
	ds_read_b128 v[40:43], v210 offset:128
	ds_read_b128 v[44:47], v210 offset:160
	s_barrier
	s_and_b64 vcc, exec, s[26:27]
	s_cbranch_vccnz .Lpq0_exit
	s_mov_b32 s4, s15
	s_branch .LBB0_795
.Lpq0_exit:
	s_cmp_lg_u32 s100, 0
	s_cbranch_scc1 .Lpq0_xa
	s_barrier
.Lpq0_xa:
	s_waitcnt lgkmcnt(13)
	v_mfma_f32_32x32x16_bf16 v[16:31], v[128:131], v[48:51], v[16:31]
	s_waitcnt lgkmcnt(12)
	v_mfma_f32_32x32x16_bf16 v[0:15], v[132:135], v[48:51], v[0:15]
	s_waitcnt lgkmcnt(11)
	v_mfma_f32_32x32x16_bf16 v[16:31], v[136:139], v[52:55], v[16:31]
	s_waitcnt lgkmcnt(10)
	v_mfma_f32_32x32x16_bf16 v[0:15], v[140:143], v[52:55], v[0:15]
	s_waitcnt lgkmcnt(9)
	v_mfma_f32_32x32x16_bf16 v[16:31], v[144:147], v[32:35], v[16:31]
	s_waitcnt lgkmcnt(8)
	v_mfma_f32_32x32x16_bf16 v[0:15], v[148:151], v[32:35], v[0:15]
	s_waitcnt lgkmcnt(7)
	v_mfma_f32_32x32x16_bf16 v[16:31], v[152:155], v[36:39], v[16:31]
	s_waitcnt lgkmcnt(6)
	v_mfma_f32_32x32x16_bf16 v[0:15], v[156:159], v[36:39], v[0:15]
	s_waitcnt lgkmcnt(0)
	s_nop 11
	s_nop 0
	s_branch .LBB0_770

; DI float bflo(unsigned u) { return __uint_as_float(u << 16); }
; DI float bfhi(unsigned u) { return __uint_as_float(u & 0xffff0000u); }
; DI f32x16 zero16() { f32x16 z; for (int i = 0; i < 16; ++i) z[i] = 0.f; return z; }
; DI void phase_attn(const Params& p, int hf, bool skipctx, char* smem, int& rot) {
;     ...
;       for (int ks = 0; ks < 6; ++ks) qu[ks] = *(const uint4*)(Qb + tq * 768 + head * 96 + ks * 16 + h * 8);
; #pragma unroll
;       for (int ks = 0; ks < 4; ++ks) {
;         const uint4 u = qu[ks];
;         qf[ks] = pack8(bflo(u.x) * QSCALE, bfhi(u.x) * QSCALE, bflo(u.y) * QSCALE, bfhi(u.y) * QSCALE, bflo(u.z) * QSCALE, bfhi(u.z) * QSCALE, bflo(u.w) * QSCALE, bfhi(u.w) * QSCALE);
;       }
;       const unsigned a1[4] = {qu[4].x, qu[4].y, qu[4].z, qu[4].w}, a2[4] = {qu[5].x, qu[5].y, qu[5].z, qu[5].w};
;       float o1[8], o2[8];
;       const int sq_ = s0 + w * 32 + r;
; #pragma unroll
;       for (int e = 0; e < 8; ++e) {
;         const float x1 = ((e & 1) ? bfhi(a1[e >> 1]) : bflo(a1[e >> 1])) * QSCALE;
;         const float x2 = ((e & 1) ? bfhi(a2[e >> 1]) : bflo(a2[e >> 1])) * QSCALE;
;         float cs = 1.f, sn = 0.f;
;         if (sq_ >= LC) { cs = axc[(sq_ - LC) * 16 + 8 * h + e]; sn = axs[(sq_ - LC) * 16 + 8 * h + e]; }
;         o1[e] = x1 * cs - x2 * sn; o2[e] = x1 * sn + x2 * cs;
;       }
;       qf[4] = pack8(o1[0], o1[1], o1[2], o1[3], o1[4], o1[5], o1[6], o1[7]);
;       qf[5] = pack8(o2[0], o2[1], o2[2], o2[3], o2[4], o2[5], o2[6], o2[7]);
;     }
;     const bf16_t* Kg = Kb + (size_t)(bl * 8 + head) * S * 96;
;     const bf16_t* Vg = VTb + (size_t)(bl * 8 + head) * 64 * S;
;     f32x16 o[2]; o[0] = zero16(); o[1] = zero16();
;     float m_run = -1e30f, l_run = 0.f;
;     uint4 ak0, ak1, ak2, av0, av1, bk0, bk1, bk2, bv0, bv1;
;     const int kr0 = tid / 12, kc0 = tid - kr0 * 12, kr1 = (tid + 512) / 12, kc1 = (tid + 512) - kr1 * 12, kr2 = (tid + 1024) / 12, kc2 = (tid + 1024) - kr2 * 12;
;     const int vr0 = tid >> 4, vr1 = (tid + 512) >> 4, vc = tid & 15;
.LBB0_1059:
	s_or_b64 exec, exec, s[26:27]
	s_waitcnt vmcnt(0)
	v_lshlrev_b32_e32 v27, 16, v23
	v_lshlrev_b32_e32 v26, 16, v19
	v_pk_mul_f32 v[26:27], v[26:27], s[48:49] op_sel_hi:[1,0]
	v_lshlrev_b32_e32 v47, 16, v22
	v_pk_mul_f32 v[28:29], v[26:27], v[30:31] op_sel:[0,1] op_sel_hi:[1,0]
	v_pk_mul_f32 v[26:27], v[26:27], v[30:31]
	v_and_b32_e32 v30, 0xffff0000, v19
	v_lshlrev_b32_e32 v46, 16, v18
	v_and_b32_e32 v19, 0xffff0000, v22
	v_and_b32_e32 v18, 0xffff0000, v18
	v_and_b32_e32 v31, 0xffff0000, v23
	v_pk_mul_f32 v[46:47], v[46:47], s[48:49] op_sel_hi:[1,0]
	v_pk_mul_f32 v[22:23], v[18:19], s[48:49] op_sel_hi:[1,0]
	v_pk_mul_f32 v[48:49], v[46:47], v[42:43] op_sel:[0,1] op_sel_hi:[1,0]
	v_pk_mul_f32 v[42:43], v[46:47], v[42:43]
	v_pk_mul_f32 v[18:19], v[22:23], v[40:41] op_sel:[0,1] op_sel_hi:[1,0]
	v_pk_mul_f32 v[22:23], v[22:23], v[40:41]
	v_mov_b32_e32 v40, v42
	v_mov_b32_e32 v41, v22
	v_mov_b32_e32 v22, v43
	v_pk_add_f32 v[22:23], v[40:41], v[22:23]
	v_lshlrev_b32_e32 v41, 16, v21
	v_lshlrev_b32_e32 v40, 16, v17
	v_pk_mul_f32 v[40:41], v[40:41], s[48:49] op_sel_hi:[1,0]
	v_mov_b32_e32 v46, v48
	v_mov_b32_e32 v47, v18
	v_mov_b32_e32 v18, v49
	v_pk_mul_f32 v[42:43], v[40:41], v[32:33] op_sel:[0,1] op_sel_hi:[1,0]
	v_pk_mul_f32 v[40:41], v[40:41], v[32:33]
	v_and_b32_e32 v33, 0xffff0000, v21
	v_and_b32_e32 v32, 0xffff0000, v17
	v_pk_add_f32 v[18:19], v[46:47], v[18:19] neg_lo:[0,1] neg_hi:[0,1]
	v_pk_mul_f32 v[46:47], v[32:33], s[48:49] op_sel_hi:[1,0]
	v_mov_b32_e32 v48, v42
	v_pk_mul_f32 v[32:33], v[46:47], v[34:35] op_sel:[0,1] op_sel_hi:[1,0]
	v_pk_mul_f32 v[34:35], v[46:47], v[34:35]
	v_mov_b32_e32 v49, v32
	v_mov_b32_e32 v32, v43
	v_mov_b32_e32 v42, v40
	v_mov_b32_e32 v43, v34
	v_mov_b32_e32 v34, v41
	v_lshlrev_b32_e32 v41, 16, v20
	v_lshlrev_b32_e32 v40, 16, v16
	v_and_b32_e32 v17, 0xffff0000, v20
	v_and_b32_e32 v16, 0xffff0000, v16
	v_pk_mul_f32 v[40:41], v[40:41], s[48:49] op_sel_hi:[1,0]
	v_pk_mul_f32 v[20:21], v[16:17], s[48:49] op_sel_hi:[1,0]
	v_pk_add_f32 v[34:35], v[42:43], v[34:35]
	v_pk_mul_f32 v[42:43], v[40:41], v[38:39] op_sel:[0,1] op_sel_hi:[1,0]
	v_pk_mul_f32 v[38:39], v[40:41], v[38:39]
	v_pk_mul_f32 v[16:17], v[20:21], v[36:37] op_sel:[0,1] op_sel_hi:[1,0]
	v_pk_mul_f32 v[20:21], v[20:21], v[36:37]
	v_mov_b32_e32 v36, v38
	v_mov_b32_e32 v37, v20
	v_mov_b32_e32 v20, v39
	v_pk_add_f32 v[20:21], v[36:37], v[20:21]
	v_lshlrev_b32_e32 v36, 16, v12
	v_and_b32_e32 v37, 0xffff0000, v12
	v_lshlrev_b32_e32 v12, 16, v13
	v_and_b32_e32 v13, 0xffff0000, v13
	v_pk_mul_f32 v[12:13], v[12:13], s[48:49] op_sel_hi:[1,0]
	v_lshlrev_b32_e32 v38, 16, v14
	v_cvt_pk_bf16_f32 v65, v12, v13
	v_lshlrev_b32_e32 v12, 16, v8
	v_and_b32_e32 v13, 0xffff0000, v8
	v_lshlrev_b32_e32 v8, 16, v9
	v_and_b32_e32 v9, 0xffff0000, v9
	v_pk_mul_f32 v[8:9], v[8:9], s[48:49] op_sel_hi:[1,0]
	v_and_b32_e32 v39, 0xffff0000, v14
	v_cvt_pk_bf16_f32 v69, v8, v9
	v_lshlrev_b32_e32 v8, 16, v4
	v_and_b32_e32 v9, 0xffff0000, v4
	v_lshlrev_b32_e32 v4, 16, v5
	v_and_b32_e32 v5, 0xffff0000, v5
	v_lshlrev_b32_e32 v14, 16, v15
	v_and_b32_e32 v15, 0xffff0000, v15
	v_pk_mul_f32 v[4:5], v[4:5], s[48:49] op_sel_hi:[1,0]
	s_mov_b32 s29, 0x2aaaaaab
	v_pk_mul_f32 v[14:15], v[14:15], s[48:49] op_sel_hi:[1,0]
	v_cvt_pk_bf16_f32 v73, v4, v5
	v_mul_hi_i32 v4, v160, s29
	v_cvt_pk_bf16_f32 v67, v14, v15
	v_lshlrev_b32_e32 v14, 16, v10
	v_and_b32_e32 v15, 0xffff0000, v10
	v_lshlrev_b32_e32 v10, 16, v11
	v_and_b32_e32 v11, 0xffff0000, v11
	v_lshrrev_b32_e32 v5, 31, v4
	v_ashrrev_i32_e32 v4, 1, v4
	v_pk_mul_f32 v[10:11], v[10:11], s[48:49] op_sel_hi:[1,0]
	v_add_u32_e32 v45, v4, v5
	v_cvt_pk_bf16_f32 v71, v10, v11
	v_lshlrev_b32_e32 v10, 16, v6
	v_and_b32_e32 v11, 0xffff0000, v6
	v_lshlrev_b32_e32 v6, 16, v7
	v_and_b32_e32 v7, 0xffff0000, v7
	v_mad_u64_u32 v[4:5], s[38:39], v45, -12, v[160:161]
	v_add_u32_e32 v164, 0x200, v160
	v_pk_mul_f32 v[6:7], v[6:7], s[48:49] op_sel_hi:[1,0]
	v_mul_hi_i32 v5, v164, s29
	v_cvt_pk_bf16_f32 v75, v6, v7
	v_lshrrev_b32_e32 v6, 31, v5
	v_ashrrev_i32_e32 v5, 1, v5
	s_mul_i32 s15, s4, 0xcc000
	v_add_u32_e32 v5, v5, v6
	v_pk_mul_f32 v[38:39], v[38:39], s[48:49] op_sel_hi:[1,0]
	v_pk_mul_f32 v[14:15], v[14:15], s[48:49] op_sel_hi:[1,0]
	s_mul_hi_i32 s5, s4, 0xcc000
	s_add_u32 s26, s90, s15
	v_mad_u64_u32 v[6:7], s[38:39], v5, -12, v[164:165]
	v_add_u32_e32 v162, 0x400, v160
	v_cvt_pk_bf16_f32 v66, v38, v39
	v_cvt_pk_bf16_f32 v70, v14, v15
	v_pk_mul_f32 v[8:9], v[8:9], s[48:49] op_sel_hi:[1,0]
	v_pk_mul_f32 v[10:11], v[10:11], s[48:49] op_sel_hi:[1,0]
	s_addc_u32 s27, s91, s5
	v_mul_hi_i32 v7, v162, s29
	v_lshlrev_b32_e32 v14, 3, v4
	v_lshlrev_b32_e32 v38, 3, v6
	v_pk_mul_f32 v[36:37], v[36:37], s[48:49] op_sel_hi:[1,0]
	v_pk_mul_f32 v[12:13], v[12:13], s[48:49] op_sel_hi:[1,0]
	v_cvt_pk_bf16_f32 v72, v8, v9
	v_cvt_pk_bf16_f32 v74, v10, v11
	v_lshrrev_b32_e32 v8, 31, v7
	v_ashrrev_i32_e32 v7, 1, v7
	v_mov_b64_e32 v[10:11], s[26:27]
	v_ashrrev_i32_e32 v15, 31, v14
	v_ashrrev_i32_e32 v39, 31, v38
	v_cvt_pk_bf16_f32 v64, v36, v37
	v_cvt_pk_bf16_f32 v68, v12, v13
	v_add_u32_e32 v7, v7, v8
	v_mad_i64_i32 v[12:13], s[26:27], v45, s17, v[10:11]
	v_lshlrev_b64 v[14:15], 1, v[14:15]
	v_mad_i64_i32 v[36:37], s[26:27], v5, s17, v[10:11]
	v_lshlrev_b64 v[38:39], 1, v[38:39]
	v_mad_u64_u32 v[8:9], s[38:39], v7, -12, v[162:163]
	v_lshl_add_u64 v[12:13], v[12:13], 0, v[14:15]
	v_lshl_add_u64 v[36:37], v[36:37], 0, v[38:39]
	s_barrier
; DI float bflo(unsigned u) { return __uint_as_float(u << 16); }
; DI float bfhi(unsigned u) { return __uint_as_float(u & 0xffff0000u); }
; DI f32x16 zero16() { f32x16 z; for (int i = 0; i < 16; ++i) z[i] = 0.f; return z; }
; DI void phase_attn(const Params& p, int hf, bool skipctx, char* smem, int& rot) {
;     ...
;       const unsigned a1[4] = {qu[4].x, qu[4].y, qu[4].z, qu[4].w}, a2[4] = {qu[5].x, qu[5].y, qu[5].z, qu[5].w};
;       float o1[8], o2[8];
;       const int sq_ = s0 + w * 32 + r;
; #pragma unroll
;       for (int e = 0; e < 8; ++e) {
;         const float x1 = ((e & 1) ? bfhi(a1[e >> 1]) : bflo(a1[e >> 1])) * QSCALE;
;         const float x2 = ((e & 1) ? bfhi(a2[e >> 1]) : bflo(a2[e >> 1])) * QSCALE;
;         float cs = 1.f, sn = 0.f;
;         if (sq_ >= LC) { cs = axc[(sq_ - LC) * 16 + 8 * h + e]; sn = axs[(sq_ - LC) * 16 + 8 * h + e]; }
;         o1[e] = x1 * cs - x2 * sn; o2[e] = x1 * sn + x2 * cs;
;       }
;       qf[4] = pack8(o1[0], o1[1], o1[2], o1[3], o1[4], o1[5], o1[6], o1[7]);
;       qf[5] = pack8(o2[0], o2[1], o2[2], o2[3], o2[4], o2[5], o2[6], o2[7]);
;     }
;     const bf16_t* Kg = Kb + (size_t)(bl * 8 + head) * S * 96;
;     const bf16_t* Vg = VTb + (size_t)(bl * 8 + head) * 64 * S;
;     f32x16 o[2]; o[0] = zero16(); o[1] = zero16();
;     float m_run = -1e30f, l_run = 0.f;
;     uint4 ak0, ak1, ak2, av0, av1, bk0, bk1, bk2, bv0, bv1;
;     const int kr0 = tid / 12, kc0 = tid - kr0 * 12, kr1 = (tid + 512) / 12, kc1 = (tid + 512) - kr1 * 12, kr2 = (tid + 1024) / 12, kc2 = (tid + 1024) - kr2 * 12;
;     const int vr0 = tid >> 4, vr1 = (tid + 512) >> 4, vc = tid & 15;
;     ...
;     ATT_LOAD(ak0, ak1, ak2, av0, av1, 0);
;     ATT_LOAD(bk0, bk1, bk2, bv0, bv1, 1);
	global_load_dwordx4 v[76:79], v[12:13], off
	global_load_dwordx4 v[80:83], v[36:37], off
	v_lshlrev_b32_e32 v36, 3, v8
	s_mul_i32 s15, s4, 0x88000
	v_readlane_b32 s36, v252, 5
	v_ashrrev_i32_e32 v37, 31, v36
	s_mul_hi_i32 s5, s4, 0x88000
	v_readlane_b32 s37, v252, 6
	s_add_u32 s36, s36, s15
	v_mad_i64_i32 v[12:13], s[26:27], v7, s17, v[10:11]
	v_lshlrev_b64 v[36:37], 1, v[36:37]
	s_addc_u32 s37, s37, s5
	v_lshl_add_u64 v[12:13], v[12:13], 0, v[36:37]
	v_mov_b32_e32 v40, v42
	v_mov_b32_e32 v41, v16
	v_mov_b32_e32 v16, v43
	v_ashrrev_i32_e32 v9, 4, v160
	v_ashrrev_i32_e32 v50, 4, v164
	global_load_dwordx4 v[84:87], v[12:13], off
	v_mov_b64_e32 v[12:13], s[36:37]
	v_lshlrev_b32_e32 v165, 4, v160
	v_cvt_pk_bf16_f32 v100, v20, v21
	v_add_u32_e32 v20, 0x80, v5
	v_pk_add_f32 v[16:17], v[40:41], v[16:17] neg_lo:[0,1] neg_hi:[0,1]
	v_mad_i64_i32 v[40:41], s[26:27], v9, s16, v[12:13]
	v_and_b32_e32 v42, 0xf0, v165
	v_mov_b32_e32 v43, v221
	v_mad_i64_i32 v[12:13], s[26:27], v50, s16, v[12:13]
	v_cvt_pk_bf16_f32 v98, v18, v19
	v_cvt_pk_bf16_f32 v102, v22, v23
	v_add_u32_e32 v18, 0x80, v45
	v_mad_i64_i32 v[20:21], s[26:27], v20, s17, v[10:11]
	v_add_u32_e32 v22, 0x80, v7
	v_lshl_add_u64 v[40:41], v[40:41], 0, v[42:43]
	v_lshl_add_u64 v[12:13], v[12:13], 0, v[42:43]
	v_mad_i64_i32 v[18:19], s[26:27], v18, s17, v[10:11]
	v_lshl_add_u64 v[20:21], v[20:21], 0, v[38:39]
	v_mad_i64_i32 v[10:11], s[26:27], v22, s17, v[10:11]
	global_load_dwordx4 v[92:95], v[40:41], off
	global_load_dwordx4 v[104:107], v[12:13], off
	v_lshl_add_u64 v[18:19], v[18:19], 0, v[14:15]
	v_lshl_add_u64 v[10:11], v[10:11], 0, v[36:37]
	global_load_dwordx4 v[108:111], v[20:21], off
	global_load_dwordx4 v[116:119], v[10:11], off
	global_load_dwordx4 v[120:123], v[40:41], off offset:256
	global_load_dwordx4 v[112:115], v[18:19], off
	global_load_dwordx4 v[124:127], v[12:13], off offset:256
	v_lshlrev_b32_e32 v46, 16, v0
	v_and_b32_e32 v47, 0xffff0000, v0
	v_lshlrev_b32_e32 v0, 16, v1
	v_and_b32_e32 v1, 0xffff0000, v1
	v_pk_mul_f32 v[30:31], v[30:31], s[48:49] op_sel_hi:[1,0]
	v_pk_add_f32 v[32:33], v[48:49], v[32:33] neg_lo:[0,1] neg_hi:[0,1]
	v_pk_mul_f32 v[0:1], v[0:1], s[48:49] op_sel_hi:[1,0]
	v_lshlrev_b32_e32 v48, 16, v2
	v_and_b32_e32 v49, 0xffff0000, v2
	v_lshlrev_b32_e32 v2, 16, v3
	v_and_b32_e32 v3, 0xffff0000, v3
	v_pk_mul_f32 v[2:3], v[2:3], s[48:49] op_sel_hi:[1,0]
	v_cvt_pk_bf16_f32 v89, v0, v1
	v_pk_mul_f32 v[0:1], v[30:31], v[24:25] op_sel:[0,1] op_sel_hi:[1,0]
	v_cvt_pk_bf16_f32 v91, v2, v3
	v_mov_b32_e32 v2, v28
	v_mov_b32_e32 v3, v0
	v_mov_b32_e32 v0, v29
	v_pk_add_f32 v[0:1], v[2:3], v[0:1] neg_lo:[0,1] neg_hi:[0,1]
	v_pk_mul_f32 v[2:3], v[30:31], v[24:25]
	v_mul_lo_u32 v10, v45, s97
	v_mov_b32_e32 v24, v26
	v_mov_b32_e32 v25, v2
	v_mov_b32_e32 v2, v27
	v_add_u32_e32 v10, 0, v10
	v_lshlrev_b32_e32 v4, 4, v4
	v_pk_add_f32 v[2:3], v[24:25], v[2:3]
	v_add_u32_e32 v176, v10, v4
	v_mul_lo_u32 v4, v5, s97
	v_cvt_pk_bf16_f32 v103, v2, v3
	v_mad_i64_i32 v[2:3], s[26:27], v5, s17, 0
	v_add_u32_e32 v4, 0, v4
	v_lshlrev_b32_e32 v5, 4, v6
	v_cvt_pk_bf16_f32 v96, v16, v17
	v_cvt_pk_bf16_f32 v99, v0, v1
	v_mad_i64_i32 v[0:1], s[26:27], v45, s17, 0
	v_mad_i64_i32 v[16:17], s[26:27], v7, s17, 0
	v_add_u32_e32 v177, v4, v5
	v_mul_lo_u32 v4, v7, s97
	v_add_u32_e32 v4, 0, v4
	v_lshlrev_b32_e32 v5, 4, v8
	s_movk_i32 s26, 0x108
	v_add_u32_e32 v178, v4, v5
	v_mul_lo_u32 v4, v9, s26
	v_add_u32_e32 v5, 0, v4
	s_movk_i32 s27, 0x6800
	v_add3_u32 v179, v5, v42, s27
	v_mul_lo_u32 v5, v50, s26
	v_add_u32_e32 v6, 0, v5
	v_add3_u32 v180, v6, v42, s27
	v_or_b32_e32 v181, 32, v161
	v_or_b32_e32 v182, 64, v161
	v_or_b32_e32 v183, 0x60, v161
	v_readlane_b32 s27, v254, 35
	v_mul_u32_u24_e32 v19, 0x108, v44
	v_mad_u32_u24 v18, v44, s97, 0
	v_add_u32_e32 v21, s27, v4
	v_add_u32_e32 v22, s27, v5
	v_add_u32_e32 v23, s27, v161
	v_add_u32_e32 v24, s27, v181
	v_mov_b32_e32 v4, s27
	v_add_u32_e32 v25, s27, v182
	v_add_u32_e32 v26, s27, v183
	v_readlane_b32 s27, v254, 36
	v_mad_u32_u24 v184, v44, s26, v4
	v_add_u32_e32 v20, 0, v161
	v_mov_b32_e32 v4, s27
	v_mad_u32_u24 v185, v44, s26, v4
	s_add_u32 s26, s15, 0x1a49c300
	v_add_u32_e32 v27, s27, v161
	v_add_u32_e32 v28, s27, v181
	v_add_u32_e32 v29, s27, v182
	v_add_u32_e32 v30, s27, v183
	s_addc_u32 s27, s5, 0
	v_mov_b64_e32 v[4:5], s[26:27]
	v_mad_i64_i32 v[166:167], s[26:27], v9, s16, v[4:5]
	v_mad_i64_i32 v[168:169], s[26:27], v50, s16, v[4:5]
	v_mad_i64_i32 v[4:5], s[26:27], s4, v231, v[16:17]
	v_mad_i64_i32 v[2:3], s[26:27], s4, v231, v[2:3]
	v_mad_i64_i32 v[0:1], s[4:5], s4, v231, v[0:1]
	v_lshl_add_u64 v[174:175], v[0:1], 0, v[14:15]
	v_mov_b32_e32 v14, v221
	v_mov_b32_e32 v15, v221
	v_add_u32_e32 v186, v21, v42
	v_add_u32_e32 v187, v22, v42
	v_add_u32_e32 v188, v23, v19
	v_add_u32_e32 v16, v24, v19
	v_add_u32_e32 v17, v25, v19
	v_add_u32_e32 v21, v26, v19
	v_add_u32_e32 v22, v28, v19
	v_add_u32_e32 v23, v29, v19
	v_add_u32_e32 v24, v30, v19
	v_pk_mul_f32 v[46:47], v[46:47], s[48:49] op_sel_hi:[1,0]
	v_pk_mul_f32 v[48:49], v[48:49], s[48:49] op_sel_hi:[1,0]
	v_lshl_add_u64 v[170:171], v[4:5], 0, v[36:37]
	v_lshl_add_u64 v[172:173], v[2:3], 0, v[38:39]
	v_mov_b32_e32 v0, v221
	v_mov_b32_e32 v1, v221
	v_mov_b32_e32 v2, v221
	v_mov_b32_e32 v3, v221
	v_mov_b32_e32 v4, v221
	v_mov_b32_e32 v5, v221
	v_mov_b32_e32 v6, v221
	v_mov_b32_e32 v7, v221
	v_mov_b32_e32 v8, v221
	v_mov_b32_e32 v9, v221
	v_mov_b32_e32 v10, v221
	v_mov_b32_e32 v11, v221
	v_mov_b32_e32 v12, v221
	v_mov_b32_e32 v13, v221
	v_add_u32_e32 v189, v27, v19
	v_add_u32_e32 v190, v18, v220
	v_add_u32_e32 v191, v20, v19
	v_add_u32_e32 v194, 0x2000, v16
	v_add_u32_e32 v204, 0x2000, v17
	v_add_u32_e32 v206, 0x2000, v21
	v_add_u32_e32 v208, 0x2000, v22
	v_add_u32_e32 v210, 0x2000, v23
	v_add_u32_e32 v211, 0x2000, v24
	v_mov_b64_e32 v[30:31], v[14:15]
	v_cvt_pk_bf16_f32 v88, v46, v47
	v_cvt_pk_bf16_f32 v90, v48, v49
	v_cvt_pk_bf16_f32 v97, v32, v33
	v_cvt_pk_bf16_f32 v101, v34, v35
	v_or_b32_e32 v166, v166, v42
	v_or_b32_e32 v168, v168, v42
	s_mov_b32 s4, 0
	v_mov_b32_e32 v212, 0xf149f2ca
	v_mov_b32_e32 v213, 0
	v_mov_b64_e32 v[28:29], v[12:13]
	v_mov_b64_e32 v[26:27], v[10:11]
	v_mov_b64_e32 v[24:25], v[8:9]
	v_mov_b64_e32 v[22:23], v[6:7]
	v_mov_b64_e32 v[20:21], v[4:5]
	v_mov_b64_e32 v[18:19], v[2:3]
	v_mov_b64_e32 v[16:17], v[0:1]
	v_and_b32_e32 v200, 15, v192
	v_lshrrev_b32_e32 v201, 4, v192
	v_mul_u32_u24_e32 v179, 0x110, v201
	v_lshrrev_b32_e32 v202, 1, v200
	v_lshl_add_u32 v179, v202, 5, v179
	v_and_b32_e32 v202, 1, v200
	v_lshl_add_u32 v179, v202, 3, v179
	v_add_u32_e32 v179, 0x6800, v179
	v_add_u32_e32 v180, 0x2200, v179
	v_add_u32_e32 v186, 0xac00, v179
	v_add_u32_e32 v187, 0xac00, v180
	v_and_b32_e32 v200, 31, v192
	v_bfe_u32 v201, v192, 5, 1
	v_mul_u32_u24_e32 v191, 0x110, v200
	v_lshl_add_u32 v191, v201, 4, v191
	v_add_u32_e32 v191, 0x6800, v191
	s_waitcnt vmcnt(9)
; DI void phase_attn(const Params& p, int hf, bool skipctx, char* smem, int& rot) {
;     ...
;     __syncthreads();
;     ATT_LOAD(ak0, ak1, ak2, av0, av1, 0);
;     ATT_LOAD(bk0, bk1, bk2, bv0, bv1, 1);
;     ATT_WRITE(ak0, ak1, ak2, av0, av1, 0);
;     __syncthreads();
	ds_write_b128 v176, v[76:79]
	s_waitcnt vmcnt(8)
	ds_write_b128 v177, v[80:83]
	s_waitcnt vmcnt(7)
	ds_write_b128 v178, v[84:87]
	s_waitcnt vmcnt(6)
	ds_write_b64 v179, v[92:93] offset:0
	ds_write_b64 v179, v[94:95] offset:16
	s_waitcnt vmcnt(5)
	ds_write_b64 v179, v[104:105] offset:8704
	ds_write_b64 v179, v[106:107] offset:8720
	s_waitcnt lgkmcnt(0)
	s_barrier
	v_mov_b32_e32 v194, v176
	v_mov_b32_e32 v204, v177
	v_mov_b32_e32 v206, v178
	v_mov_b32_e32 v208, v179
	v_mov_b32_e32 v210, v190
	v_mov_b32_e32 v211, v191
	v_mov_b32_e32 v220, 0xf149f2ca
	v_mov_b32_e32 v176, 0
	v_mov_b32_e32 v177, 0
	v_mov_b32_e32 v178, 0
	v_mov_b32_e32 v179, 0
	v_mov_b32_e32 v180, 0
	v_mov_b32_e32 v181, 0
	v_mov_b32_e32 v182, 0
	v_mov_b32_e32 v183, 0
	v_mov_b32_e32 v184, 0
	v_mov_b32_e32 v185, 0
	v_mov_b32_e32 v186, 0
	v_mov_b32_e32 v187, 0
	v_mov_b32_e32 v188, 0
	v_mov_b32_e32 v189, 0
	v_mov_b32_e32 v190, 0
	v_mov_b32_e32 v191, 0
	v_mov_b32_e32 v32, 0
	v_mov_b32_e32 v33, 0
	v_mov_b32_e32 v34, 0
	v_mov_b32_e32 v35, 0
	v_mov_b32_e32 v36, 0
	v_mov_b32_e32 v37, 0
	v_mov_b32_e32 v38, 0
	v_mov_b32_e32 v39, 0
	v_mov_b32_e32 v48, 0
	v_mov_b32_e32 v49, 0
	v_mov_b32_e32 v50, 0
	v_mov_b32_e32 v51, 0
	v_mov_b32_e32 v52, 0
	v_mov_b32_e32 v53, 0
	v_mov_b32_e32 v54, 0
	v_mov_b32_e32 v55, 0
	v_mov_b32_e32 v128, 0
	v_mov_b32_e32 v129, 0
	v_mov_b32_e32 v130, 0
	v_mov_b32_e32 v131, 0
	v_mov_b32_e32 v132, 0
	v_mov_b32_e32 v133, 0
	v_mov_b32_e32 v134, 0
	v_mov_b32_e32 v135, 0
	v_mov_b32_e32 v136, 0
	v_mov_b32_e32 v137, 0
	v_mov_b32_e32 v138, 0
	v_mov_b32_e32 v139, 0
	v_mov_b32_e32 v140, 0
	v_mov_b32_e32 v141, 0
	v_mov_b32_e32 v142, 0
	v_mov_b32_e32 v143, 0
	v_mov_b32_e32 v144, 0
	v_mov_b32_e32 v145, 0
	v_mov_b32_e32 v146, 0
	v_mov_b32_e32 v147, 0
	v_mov_b32_e32 v148, 0
	v_mov_b32_e32 v149, 0
	v_mov_b32_e32 v150, 0
	v_mov_b32_e32 v151, 0
	v_mov_b32_e32 v152, 0
	v_mov_b32_e32 v153, 0
	v_mov_b32_e32 v154, 0
	v_mov_b32_e32 v155, 0
	v_mov_b32_e32 v156, 0
	v_mov_b32_e32 v157, 0
	v_mov_b32_e32 v158, 0
	v_mov_b32_e32 v159, 0
	ds_read_b128 v[214:217], v210 offset:0
	ds_read_b128 v[234:237], v210 offset:32
	ds_read_b128 v[238:241], v210 offset:64
	ds_read_b128 v[242:245], v210 offset:96
	ds_read_b128 v[40:43], v210 offset:128
	ds_read_b128 v[44:47], v210 offset:160
	s_cmp_eq_u32 s100, 0
	s_cbranch_scc1 .Lpq1_eb
	s_barrier

; __global__ void __launch_bounds__(NT, 2) fwd_megakernel(Params p) {
	.amdhsa_kernel _Z14fwd_megakernel6Params
		.amdhsa_group_segment_fixed_size 0
		.amdhsa_private_segment_fixed_size 0
		.amdhsa_kernarg_size 496
		.amdhsa_user_sgpr_count 2
		.amdhsa_user_sgpr_dispatch_ptr 0
		.amdhsa_user_sgpr_queue_ptr 0
		.amdhsa_user_sgpr_kernarg_segment_ptr 1
		.amdhsa_user_sgpr_dispatch_id 0
		.amdhsa_user_sgpr_kernarg_preload_length 0
		.amdhsa_user_sgpr_kernarg_preload_offset 0
		.amdhsa_user_sgpr_private_segment_size 0
		.amdhsa_uses_dynamic_stack 0
		.amdhsa_enable_private_segment 0
		.amdhsa_system_sgpr_workgroup_id_x 1
		.amdhsa_system_sgpr_workgroup_id_y 0
		.amdhsa_system_sgpr_workgroup_id_z 0
		.amdhsa_system_sgpr_workgroup_info 0
		.amdhsa_system_vgpr_workitem_id 2
		.amdhsa_next_free_vgpr 256
		.amdhsa_next_free_sgpr 102
		.amdhsa_accum_offset 256
		.amdhsa_reserve_vcc 1
		.amdhsa_float_round_mode_32 0
		.amdhsa_float_round_mode_16_64 0
		.amdhsa_float_denorm_mode_32 3
		.amdhsa_float_denorm_mode_16_64 3
		.amdhsa_dx10_clamp 1
		.amdhsa_ieee_mode 1
		.amdhsa_fp16_overflow 0
		.amdhsa_tg_split 0
		.amdhsa_exception_fp_ieee_invalid_op 0
		.amdhsa_exception_fp_denorm_src 0
		.amdhsa_exception_fp_ieee_div_zero 0
		.amdhsa_exception_fp_ieee_overflow 0
		.amdhsa_exception_fp_ieee_underflow 0
		.amdhsa_exception_fp_ieee_inexact 0
		.amdhsa_exception_int_div_zero 0
	.end_amdhsa_kernel

; __global__ void __launch_bounds__(NT, 2) fwd_megakernel(Params p) {
amdhsa.kernels:
  - .agpr_count:     0
    .args:
      - .offset:         0
        .size:           240
        .value_kind:     by_value
      - .offset:         240
        .size:           4
        .value_kind:     hidden_block_count_x
      - .offset:         244
        .size:           4
        .value_kind:     hidden_block_count_y
      - .offset:         248
        .size:           4
        .value_kind:     hidden_block_count_z
      - .offset:         252
        .size:           2
        .value_kind:     hidden_group_size_x
      - .offset:         254
        .size:           2
        .value_kind:     hidden_group_size_y
      - .offset:         256
        .size:           2
        .value_kind:     hidden_group_size_z
      - .offset:         258
        .size:           2
        .value_kind:     hidden_remainder_x
      - .offset:         260
        .size:           2
        .value_kind:     hidden_remainder_y
      - .offset:         262
        .size:           2
        .value_kind:     hidden_remainder_z
      - .offset:         280
        .size:           8
        .value_kind:     hidden_global_offset_x
      - .offset:         288
        .size:           8
        .value_kind:     hidden_global_offset_y
      - .offset:         296
        .size:           8
        .value_kind:     hidden_global_offset_z
      - .offset:         304
        .size:           2
        .value_kind:     hidden_grid_dims
      - .offset:         328
        .size:           8
        .value_kind:     hidden_multigrid_sync_arg
      - .offset:         360
        .size:           4
        .value_kind:     hidden_dynamic_lds_size
    .group_segment_fixed_size: 0
    .kernarg_segment_align: 8
    .kernarg_segment_size: 496
    .language:       OpenCL C
    .language_version:
      - 2
      - 0
    .max_flat_workgroup_size: 512
    .name:           _Z14fwd_megakernel6Params
    .private_segment_fixed_size: 0
    .sgpr_count:     108
    .sgpr_spill_count: 399
    .symbol:         _Z14fwd_megakernel6Params.kd
    .uniform_work_group_size: 1
    .uses_dynamic_stack: false
    .vgpr_count:     256
    .vgpr_spill_count: 0
    .wavefront_size: 64
